# K-loop trim: drop redundant lgkmcnt(0) after barrier and the mid-segment setprio 0/1 pair in the 5 full GEMM loops
# baseline (speedup 1.0000x reference)
; #define PG8_STAGE(bufoff, gbase, voff) do { _Pragma("unroll") for (int _i = 0; _i < 2; ++_i) \
;         __builtin_amdgcn_global_load_lds((const unsigned*)((const char*)(gbase) + (voff)[_i]), (LAS unsigned*)(lds + (bufoff) + ldsw + _i * 8192), 16, 0, 0); } while (0)
; #define PG8_LDA(dst, b, h) do { _Pragma("unroll") for (int m = 0; m < 4; ++m) _Pragma("unroll") for (int k = 0; k < 2; ++k) dst[m][k] = *(const LAS bf16x8*)(lds + PG8_SA(b, h) + aoff + m * 2048 + k * 1024); } while (0)
; #define PG8_LDB(dst, b, h) do { _Pragma("unroll") for (int n = 0; n < 2; ++n) _Pragma("unroll") for (int k = 0; k < 2; ++k) dst[n][k] = *(const LAS bf16x8*)(lds + PG8_SB(b, h) + boff + n * 2048 + k * 1024); } while (0)
; #define PG8_MMA(ai, bj, At, Bt) do { __builtin_amdgcn_s_setprio(1); _Pragma("unroll") for (int m = 0; m < 4; ++m) _Pragma("unroll") for (int n = 0; n < 2; ++n) _Pragma("unroll") for (int k = 0; k < 2; ++k) \
;         acc[ai][bj][m][n] = __builtin_amdgcn_mfma_f32_16x16x32_bf16(Bt[n][k], At[m][k], acc[ai][bj][m][n], 0, 0, 0); __builtin_amdgcn_s_setprio(0); } while (0)
; #define PG8_WAIT_V(n) asm volatile("s_waitcnt vmcnt(" #n ")" ::: "memory")
; #define PG8_WAIT_L(n) asm volatile("s_waitcnt lgkmcnt(" #n ")" ::: "memory")
; #define PG8_BAR __builtin_amdgcn_s_barrier()
; template <class Epi, class Sched>
; __device__ __forceinline__ void gemm_phase(LAS unsigned char* lds, const Gemm g, const Sched& S, const Epi& E) {
;     ...
;         for (int t = 0; t < nt; t += 2) {
;             const bool last = (t == nt - 2);
;             const char* a1 = cA + (size_t)(t + 1) * kstep;
;             const char* a2 = last ? nA : cA + (size_t)(t + 2) * kstep; const char* b2 = last ? nB : cB + (size_t)(t + 2) * kstep;
;             const char* a3 = a2 + kstep; const char* b3 = b2 + kstep;
;             if (last && has_next) S.a_ready(nxt);
;             PG8_LDB(B0, 0, 0); PG8_LDB(B1, 0, 1); PG8_SCHED; PG8_LDA(At, 0, 0); PG8_STAGE(PG8_SA(1, 1), a1 + hstepA, voffA);
;             PG8_WAIT_V(8); PG8_WAIT_L(0); PG8_BAR; PG8_MMA(0, 0, At, B0); PG8_MMA(0, 1, At, B1); PG8_BAR; PG8_SCHED;
;             PG8_LDA(At, 0, 1); PG8_STAGE(PG8_SB(0, 0), b2, voffB); PG8_STAGE(PG8_SB(0, 1), b2 + hstepB, voffB); PG8_STAGE(PG8_SA(0, 0), a2, voffA);
;             PG8_WAIT_V(8); PG8_WAIT_L(0); PG8_BAR; PG8_MMA(1, 0, At, B0); PG8_MMA(1, 1, At, B1); PG8_BAR; PG8_SCHED;
.LBB0_137:
	s_add_u32 s28, s26, 0xfff80080
	s_addc_u32 s29, s27, -1
	s_add_i32 s60, 0, 0x10000
	s_cmp_eq_u32 s59, 28
	s_cselect_b32 s41, s21, s29
	s_cselect_b32 s40, s55, s28
	s_cselect_b32 s29, s19, s58
	s_cselect_b32 s28, s56, s57
	s_add_i32 s62, 0, 0x14000
	v_add_u32_e32 v154, s60, v159
	v_add_u32_e32 v174, s62, v159
	ds_read_b128 v[142:145], v154
	ds_read_b128 v[146:149], v154 offset:1024
	ds_read_b128 v[150:153], v154 offset:2048
	ds_read_b128 v[154:157], v154 offset:3072
	ds_read_b128 v[162:165], v174
	ds_read_b128 v[166:169], v174 offset:1024
	ds_read_b128 v[170:173], v174 offset:2048
	ds_read_b128 v[174:177], v174 offset:3072
	v_lshl_add_u64 v[224:225], s[26:27], 0, v[138:139]
	s_add_i32 m0, s46, 0xc000
	ds_read_b128 v[178:181], v161
	ds_read_b128 v[182:185], v161 offset:1024
	ds_read_b128 v[186:189], v161 offset:2048
	ds_read_b128 v[190:193], v161 offset:3072
	ds_read_b128 v[194:197], v161 offset:4096
	ds_read_b128 v[212:215], v161 offset:5120
	ds_read_b128 v[216:219], v161 offset:6144
	ds_read_b128 v[220:223], v161 offset:7168
	global_load_lds_dwordx4 v[224:225], off
	v_lshl_add_u64 v[224:225], s[26:27], 0, v[140:141]
	s_add_i32 m0, s46, 0xe000
	s_nop 0
	global_load_lds_dwordx4 v[224:225], off
	s_waitcnt vmcnt(8)
	s_waitcnt lgkmcnt(0)
	s_barrier
	s_setprio 1
	v_mfma_f32_16x16x32_bf16 v[130:133], v[142:145], v[178:181], v[130:133]
	v_mfma_f32_16x16x32_bf16 v[122:125], v[150:153], v[178:181], v[122:125]
	v_mfma_f32_16x16x32_bf16 v[114:117], v[142:145], v[186:189], v[114:117]
	v_mfma_f32_16x16x32_bf16 v[106:109], v[150:153], v[186:189], v[106:109]
	v_mfma_f32_16x16x32_bf16 v[98:101], v[142:145], v[194:197], v[98:101]
	v_mfma_f32_16x16x32_bf16 v[90:93], v[150:153], v[194:197], v[90:93]
	v_mfma_f32_16x16x32_bf16 v[82:85], v[142:145], v[216:219], v[82:85]
	v_mfma_f32_16x16x32_bf16 v[74:77], v[150:153], v[216:219], v[74:77]
	v_mfma_f32_16x16x32_bf16 v[130:133], v[146:149], v[182:185], v[130:133]
	v_mfma_f32_16x16x32_bf16 v[122:125], v[154:157], v[182:185], v[122:125]
	v_mfma_f32_16x16x32_bf16 v[114:117], v[146:149], v[190:193], v[114:117]
	v_mfma_f32_16x16x32_bf16 v[106:109], v[154:157], v[190:193], v[106:109]
	v_mfma_f32_16x16x32_bf16 v[98:101], v[146:149], v[212:215], v[98:101]
	v_mfma_f32_16x16x32_bf16 v[90:93], v[154:157], v[212:215], v[90:93]
	v_mfma_f32_16x16x32_bf16 v[82:85], v[146:149], v[220:223], v[82:85]
	v_mfma_f32_16x16x32_bf16 v[74:77], v[154:157], v[220:223], v[74:77]
	v_mfma_f32_16x16x32_bf16 v[126:129], v[162:165], v[178:181], v[126:129]
	v_mfma_f32_16x16x32_bf16 v[118:121], v[170:173], v[178:181], v[118:121]
	v_mfma_f32_16x16x32_bf16 v[110:113], v[162:165], v[186:189], v[110:113]
	v_mfma_f32_16x16x32_bf16 v[102:105], v[170:173], v[186:189], v[102:105]
	v_mfma_f32_16x16x32_bf16 v[94:97], v[162:165], v[194:197], v[94:97]
	v_mfma_f32_16x16x32_bf16 v[86:89], v[170:173], v[194:197], v[86:89]
	v_mfma_f32_16x16x32_bf16 v[78:81], v[162:165], v[216:219], v[78:81]
	v_mfma_f32_16x16x32_bf16 v[70:73], v[170:173], v[216:219], v[70:73]
	v_mfma_f32_16x16x32_bf16 v[126:129], v[166:169], v[182:185], v[126:129]
	v_mfma_f32_16x16x32_bf16 v[118:121], v[174:177], v[182:185], v[118:121]
	v_mfma_f32_16x16x32_bf16 v[110:113], v[166:169], v[190:193], v[110:113]
	v_mfma_f32_16x16x32_bf16 v[102:105], v[174:177], v[190:193], v[102:105]
	v_mfma_f32_16x16x32_bf16 v[94:97], v[166:169], v[212:215], v[94:97]
	v_mfma_f32_16x16x32_bf16 v[86:89], v[174:177], v[212:215], v[86:89]
	v_mfma_f32_16x16x32_bf16 v[78:81], v[166:169], v[220:223], v[78:81]
	v_mfma_f32_16x16x32_bf16 v[70:73], v[174:177], v[220:223], v[70:73]
	s_setprio 0
	s_barrier
	s_add_i32 s60, s60, s45
	v_lshl_add_u64 v[224:225], s[28:29], 0, v[4:5]
	s_mov_b32 m0, s60
	ds_read_b128 v[178:181], v161 offset:16384
	ds_read_b128 v[182:185], v161 offset:17408
	ds_read_b128 v[186:189], v161 offset:18432
	ds_read_b128 v[190:193], v161 offset:19456
	ds_read_b128 v[194:197], v161 offset:20480
	ds_read_b128 v[212:215], v161 offset:21504
	ds_read_b128 v[216:219], v161 offset:22528
	ds_read_b128 v[220:223], v161 offset:23552
	global_load_lds_dwordx4 v[224:225], off
	s_add_i32 m0, s60, 0x2000
	s_add_u32 s60, s28, 0x80000
	v_lshl_add_u64 v[226:227], s[28:29], 0, v[2:3]
	s_addc_u32 s61, s29, 0
	s_add_i32 s62, s62, s45
	global_load_lds_dwordx4 v[226:227], off
	v_lshl_add_u64 v[228:229], s[60:61], 0, v[4:5]
	s_mov_b32 m0, s62
	v_lshl_add_u64 v[230:231], s[40:41], 0, v[134:135]
	global_load_lds_dwordx4 v[228:229], off
	v_lshl_add_u64 v[228:229], s[60:61], 0, v[2:3]
	s_add_i32 m0, s62, 0x2000
	s_nop 0
	global_load_lds_dwordx4 v[228:229], off
	v_lshl_add_u64 v[228:229], s[40:41], 0, v[136:137]
	s_mov_b32 m0, s46
	s_nop 0
	global_load_lds_dwordx4 v[228:229], off
	s_mov_b32 m0, s47
	s_nop 0
	global_load_lds_dwordx4 v[230:231], off
	s_waitcnt vmcnt(8)
	s_waitcnt lgkmcnt(0)
	s_barrier
; #define PG8_STAGE(bufoff, gbase, voff) do { _Pragma("unroll") for (int _i = 0; _i < 2; ++_i) \
;         __builtin_amdgcn_global_load_lds((const unsigned*)((const char*)(gbase) + (voff)[_i]), (LAS unsigned*)(lds + (bufoff) + ldsw + _i * 8192), 16, 0, 0); } while (0)
; #define PG8_LDA(dst, b, h) do { _Pragma("unroll") for (int m = 0; m < 4; ++m) _Pragma("unroll") for (int k = 0; k < 2; ++k) dst[m][k] = *(const LAS bf16x8*)(lds + PG8_SA(b, h) + aoff + m * 2048 + k * 1024); } while (0)
; #define PG8_LDB(dst, b, h) do { _Pragma("unroll") for (int n = 0; n < 2; ++n) _Pragma("unroll") for (int k = 0; k < 2; ++k) dst[n][k] = *(const LAS bf16x8*)(lds + PG8_SB(b, h) + boff + n * 2048 + k * 1024); } while (0)
; #define PG8_MMA(ai, bj, At, Bt) do { __builtin_amdgcn_s_setprio(1); _Pragma("unroll") for (int m = 0; m < 4; ++m) _Pragma("unroll") for (int n = 0; n < 2; ++n) _Pragma("unroll") for (int k = 0; k < 2; ++k) \
;         acc[ai][bj][m][n] = __builtin_amdgcn_mfma_f32_16x16x32_bf16(Bt[n][k], At[m][k], acc[ai][bj][m][n], 0, 0, 0); __builtin_amdgcn_s_setprio(0); } while (0)
; #define PG8_WAIT_V(n) asm volatile("s_waitcnt vmcnt(" #n ")" ::: "memory")
; #define PG8_WAIT_L(n) asm volatile("s_waitcnt lgkmcnt(" #n ")" ::: "memory")
; #define PG8_BAR __builtin_amdgcn_s_barrier()
; #define PG8_SCHED __builtin_amdgcn_sched_barrier(0)
; template <class Epi, class Sched>
; __device__ __forceinline__ void gemm_phase(LAS unsigned char* lds, const Gemm g, const Sched& S, const Epi& E) {
;     ...
;             PG8_WAIT_V(8); PG8_WAIT_L(0); PG8_BAR; PG8_MMA(1, 0, At, B0); PG8_MMA(1, 1, At, B1); PG8_BAR; PG8_SCHED;
;             PG8_LDB(B0, 1, 0); PG8_LDB(B1, 1, 1); PG8_SCHED; PG8_LDA(At, 1, 0); PG8_STAGE(PG8_SA(0, 1), a2 + hstepA, voffA);
;             PG8_WAIT_V(8); PG8_WAIT_L(0); PG8_BAR; PG8_MMA(0, 0, At, B0); PG8_MMA(0, 1, At, B1); PG8_BAR; PG8_SCHED;
	s_setprio 1
	v_mfma_f32_16x16x32_bf16 v[66:69], v[142:145], v[178:181], v[66:69]
	v_mfma_f32_16x16x32_bf16 v[58:61], v[150:153], v[178:181], v[58:61]
	v_mfma_f32_16x16x32_bf16 v[50:53], v[142:145], v[186:189], v[50:53]
	v_mfma_f32_16x16x32_bf16 v[42:45], v[150:153], v[186:189], v[42:45]
	v_mfma_f32_16x16x32_bf16 v[34:37], v[142:145], v[194:197], v[34:37]
	v_mfma_f32_16x16x32_bf16 v[26:29], v[150:153], v[194:197], v[26:29]
	v_mfma_f32_16x16x32_bf16 v[18:21], v[142:145], v[216:219], v[18:21]
	v_mfma_f32_16x16x32_bf16 v[10:13], v[150:153], v[216:219], v[10:13]
	v_mfma_f32_16x16x32_bf16 v[66:69], v[146:149], v[182:185], v[66:69]
	v_mfma_f32_16x16x32_bf16 v[58:61], v[154:157], v[182:185], v[58:61]
	v_mfma_f32_16x16x32_bf16 v[50:53], v[146:149], v[190:193], v[50:53]
	v_mfma_f32_16x16x32_bf16 v[42:45], v[154:157], v[190:193], v[42:45]
	v_mfma_f32_16x16x32_bf16 v[34:37], v[146:149], v[212:215], v[34:37]
	v_mfma_f32_16x16x32_bf16 v[26:29], v[154:157], v[212:215], v[26:29]
	v_mfma_f32_16x16x32_bf16 v[18:21], v[146:149], v[220:223], v[18:21]
	v_mfma_f32_16x16x32_bf16 v[10:13], v[154:157], v[220:223], v[10:13]
	v_mfma_f32_16x16x32_bf16 v[62:65], v[162:165], v[178:181], v[62:65]
	v_mfma_f32_16x16x32_bf16 v[54:57], v[170:173], v[178:181], v[54:57]
	v_mfma_f32_16x16x32_bf16 v[46:49], v[162:165], v[186:189], v[46:49]
	v_mfma_f32_16x16x32_bf16 v[38:41], v[170:173], v[186:189], v[38:41]
	v_mfma_f32_16x16x32_bf16 v[30:33], v[162:165], v[194:197], v[30:33]
	v_mfma_f32_16x16x32_bf16 v[22:25], v[170:173], v[194:197], v[22:25]
	v_mfma_f32_16x16x32_bf16 v[14:17], v[162:165], v[216:219], v[14:17]
	v_mfma_f32_16x16x32_bf16 v[6:9], v[170:173], v[216:219], v[6:9]
	v_mfma_f32_16x16x32_bf16 v[62:65], v[166:169], v[182:185], v[62:65]
	v_mfma_f32_16x16x32_bf16 v[54:57], v[174:177], v[182:185], v[54:57]
	v_mfma_f32_16x16x32_bf16 v[46:49], v[166:169], v[190:193], v[46:49]
	v_mfma_f32_16x16x32_bf16 v[38:41], v[174:177], v[190:193], v[38:41]
	v_mfma_f32_16x16x32_bf16 v[30:33], v[166:169], v[212:215], v[30:33]
	v_mfma_f32_16x16x32_bf16 v[22:25], v[174:177], v[212:215], v[22:25]
	v_mfma_f32_16x16x32_bf16 v[14:17], v[166:169], v[220:223], v[14:17]
	v_mfma_f32_16x16x32_bf16 v[6:9], v[174:177], v[220:223], v[6:9]
	s_setprio 0
	s_barrier
	s_add_i32 s60, 0, 0x18000
	s_add_i32 s61, 0, 0x1c000
	v_add_u32_e32 v154, s60, v159
	v_add_u32_e32 v174, s61, v159
	ds_read_b128 v[142:145], v154
	ds_read_b128 v[146:149], v154 offset:1024
	ds_read_b128 v[150:153], v154 offset:2048
	ds_read_b128 v[154:157], v154 offset:3072
	ds_read_b128 v[162:165], v174
	ds_read_b128 v[166:169], v174 offset:1024
	ds_read_b128 v[170:173], v174 offset:2048
	ds_read_b128 v[174:177], v174 offset:3072
	s_add_u32 s40, s40, 0x80000
	s_addc_u32 s41, s41, 0
	s_mov_b32 m0, s48
	v_lshl_add_u64 v[236:237], s[40:41], 0, v[136:137]
	ds_read_b128 v[178:181], v161 offset:32768
	ds_read_b128 v[182:185], v161 offset:33792
	ds_read_b128 v[186:189], v161 offset:34816
	ds_read_b128 v[190:193], v161 offset:35840
	ds_read_b128 v[194:197], v161 offset:36864
	ds_read_b128 v[212:215], v161 offset:37888
	ds_read_b128 v[216:219], v161 offset:38912
	ds_read_b128 v[220:223], v161 offset:39936
	global_load_lds_dwordx4 v[236:237], off
	v_lshl_add_u64 v[236:237], s[40:41], 0, v[134:135]
	s_mov_b32 m0, s49
	s_nop 0
	global_load_lds_dwordx4 v[236:237], off
	s_waitcnt vmcnt(8)
	s_waitcnt lgkmcnt(0)
	s_barrier
	s_setprio 1
	v_mfma_f32_16x16x32_bf16 v[130:133], v[142:145], v[178:181], v[130:133]
	v_mfma_f32_16x16x32_bf16 v[122:125], v[150:153], v[178:181], v[122:125]
	v_mfma_f32_16x16x32_bf16 v[114:117], v[142:145], v[186:189], v[114:117]
	v_mfma_f32_16x16x32_bf16 v[106:109], v[150:153], v[186:189], v[106:109]
	v_mfma_f32_16x16x32_bf16 v[98:101], v[142:145], v[194:197], v[98:101]
	v_mfma_f32_16x16x32_bf16 v[90:93], v[150:153], v[194:197], v[90:93]
	v_mfma_f32_16x16x32_bf16 v[82:85], v[142:145], v[216:219], v[82:85]
	v_mfma_f32_16x16x32_bf16 v[74:77], v[150:153], v[216:219], v[74:77]
	v_mfma_f32_16x16x32_bf16 v[130:133], v[146:149], v[182:185], v[130:133]
	v_mfma_f32_16x16x32_bf16 v[122:125], v[154:157], v[182:185], v[122:125]
	v_mfma_f32_16x16x32_bf16 v[114:117], v[146:149], v[190:193], v[114:117]
	v_mfma_f32_16x16x32_bf16 v[106:109], v[154:157], v[190:193], v[106:109]
	v_mfma_f32_16x16x32_bf16 v[98:101], v[146:149], v[212:215], v[98:101]
	v_mfma_f32_16x16x32_bf16 v[90:93], v[154:157], v[212:215], v[90:93]
	v_mfma_f32_16x16x32_bf16 v[82:85], v[146:149], v[220:223], v[82:85]
	v_mfma_f32_16x16x32_bf16 v[74:77], v[154:157], v[220:223], v[74:77]
	v_mfma_f32_16x16x32_bf16 v[126:129], v[162:165], v[178:181], v[126:129]
	v_mfma_f32_16x16x32_bf16 v[118:121], v[170:173], v[178:181], v[118:121]
	v_mfma_f32_16x16x32_bf16 v[110:113], v[162:165], v[186:189], v[110:113]
	v_mfma_f32_16x16x32_bf16 v[102:105], v[170:173], v[186:189], v[102:105]
	v_mfma_f32_16x16x32_bf16 v[94:97], v[162:165], v[194:197], v[94:97]
	v_mfma_f32_16x16x32_bf16 v[86:89], v[170:173], v[194:197], v[86:89]
	v_mfma_f32_16x16x32_bf16 v[78:81], v[162:165], v[216:219], v[78:81]
	v_mfma_f32_16x16x32_bf16 v[70:73], v[170:173], v[216:219], v[70:73]
	v_mfma_f32_16x16x32_bf16 v[126:129], v[166:169], v[182:185], v[126:129]
	v_mfma_f32_16x16x32_bf16 v[118:121], v[174:177], v[182:185], v[118:121]
	v_mfma_f32_16x16x32_bf16 v[110:113], v[166:169], v[190:193], v[110:113]
	v_mfma_f32_16x16x32_bf16 v[102:105], v[174:177], v[190:193], v[102:105]
	v_mfma_f32_16x16x32_bf16 v[94:97], v[166:169], v[212:215], v[94:97]
	v_mfma_f32_16x16x32_bf16 v[86:89], v[174:177], v[212:215], v[86:89]
	v_mfma_f32_16x16x32_bf16 v[78:81], v[166:169], v[220:223], v[78:81]
	v_mfma_f32_16x16x32_bf16 v[70:73], v[174:177], v[220:223], v[70:73]
	s_setprio 0
	s_barrier
; #define PG8_STAGE(bufoff, gbase, voff) do { _Pragma("unroll") for (int _i = 0; _i < 2; ++_i) \
;         __builtin_amdgcn_global_load_lds((const unsigned*)((const char*)(gbase) + (voff)[_i]), (LAS unsigned*)(lds + (bufoff) + ldsw + _i * 8192), 16, 0, 0); } while (0)
; #define PG8_LDA(dst, b, h) do { _Pragma("unroll") for (int m = 0; m < 4; ++m) _Pragma("unroll") for (int k = 0; k < 2; ++k) dst[m][k] = *(const LAS bf16x8*)(lds + PG8_SA(b, h) + aoff + m * 2048 + k * 1024); } while (0)
; #define PG8_MMA(ai, bj, At, Bt) do { __builtin_amdgcn_s_setprio(1); _Pragma("unroll") for (int m = 0; m < 4; ++m) _Pragma("unroll") for (int n = 0; n < 2; ++n) _Pragma("unroll") for (int k = 0; k < 2; ++k) \
;         acc[ai][bj][m][n] = __builtin_amdgcn_mfma_f32_16x16x32_bf16(Bt[n][k], At[m][k], acc[ai][bj][m][n], 0, 0, 0); __builtin_amdgcn_s_setprio(0); } while (0)
; #define PG8_WAIT_V(n) asm volatile("s_waitcnt vmcnt(" #n ")" ::: "memory")
; #define PG8_WAIT_L(n) asm volatile("s_waitcnt lgkmcnt(" #n ")" ::: "memory")
; #define PG8_BAR __builtin_amdgcn_s_barrier()
; #define PG8_SCHED __builtin_amdgcn_sched_barrier(0)
; template <class Epi, class Sched>
; __device__ __forceinline__ void gemm_phase(LAS unsigned char* lds, const Gemm g, const Sched& S, const Epi& E) {
;     ...
;             PG8_LDA(At, 1, 1); PG8_STAGE(PG8_SB(1, 0), b3, voffB); PG8_STAGE(PG8_SB(1, 1), b3 + hstepB, voffB); PG8_STAGE(PG8_SA(1, 0), a3, voffA);
;             PG8_WAIT_V(8); PG8_WAIT_L(0); PG8_BAR; PG8_MMA(1, 0, At, B0); PG8_MMA(1, 1, At, B1); PG8_BAR; PG8_SCHED;
;         }
;         if (wr == 0) PG8_BAR;
	s_add_i32 s40, s60, s45
	v_lshl_add_u64 v[224:225], v[224:225], 0, s[36:37]
	s_mov_b32 m0, s40
	ds_read_b128 v[178:181], v161 offset:49152
	ds_read_b128 v[182:185], v161 offset:50176
	ds_read_b128 v[186:189], v161 offset:51200
	ds_read_b128 v[190:193], v161 offset:52224
	ds_read_b128 v[194:197], v161 offset:53248
	ds_read_b128 v[212:215], v161 offset:54272
	ds_read_b128 v[216:219], v161 offset:55296
	ds_read_b128 v[220:223], v161 offset:56320
	global_load_lds_dwordx4 v[224:225], off
	s_add_i32 m0, s40, 0x2000
	s_add_u32 s28, s28, 0x80080
	v_lshl_add_u64 v[224:225], v[226:227], 0, s[36:37]
	s_addc_u32 s29, s29, 0
	s_add_i32 s40, s61, s45
	global_load_lds_dwordx4 v[224:225], off
	v_lshl_add_u64 v[224:225], s[28:29], 0, v[4:5]
	s_mov_b32 m0, s40
	s_nop 0
	global_load_lds_dwordx4 v[224:225], off
	v_lshl_add_u64 v[224:225], s[28:29], 0, v[2:3]
	s_add_i32 m0, s40, 0x2000
	s_nop 0
	global_load_lds_dwordx4 v[224:225], off
	v_lshl_add_u64 v[224:225], v[228:229], 0, s[36:37]
	s_mov_b32 m0, s50
	s_nop 0
	global_load_lds_dwordx4 v[224:225], off
	v_lshl_add_u64 v[224:225], v[230:231], 0, s[36:37]
	s_mov_b32 m0, s51
	s_nop 0
	global_load_lds_dwordx4 v[224:225], off
	s_waitcnt vmcnt(8)
	s_waitcnt lgkmcnt(0)
	s_barrier
	s_setprio 1
	v_mfma_f32_16x16x32_bf16 v[66:69], v[142:145], v[178:181], v[66:69]
	v_mfma_f32_16x16x32_bf16 v[58:61], v[150:153], v[178:181], v[58:61]
	v_mfma_f32_16x16x32_bf16 v[50:53], v[142:145], v[186:189], v[50:53]
	v_mfma_f32_16x16x32_bf16 v[42:45], v[150:153], v[186:189], v[42:45]
	v_mfma_f32_16x16x32_bf16 v[34:37], v[142:145], v[194:197], v[34:37]
	v_mfma_f32_16x16x32_bf16 v[26:29], v[150:153], v[194:197], v[26:29]
	v_mfma_f32_16x16x32_bf16 v[18:21], v[142:145], v[216:219], v[18:21]
	v_mfma_f32_16x16x32_bf16 v[10:13], v[150:153], v[216:219], v[10:13]
	v_mfma_f32_16x16x32_bf16 v[66:69], v[146:149], v[182:185], v[66:69]
	v_mfma_f32_16x16x32_bf16 v[58:61], v[154:157], v[182:185], v[58:61]
	v_mfma_f32_16x16x32_bf16 v[50:53], v[146:149], v[190:193], v[50:53]
	v_mfma_f32_16x16x32_bf16 v[42:45], v[154:157], v[190:193], v[42:45]
	v_mfma_f32_16x16x32_bf16 v[34:37], v[146:149], v[212:215], v[34:37]
	v_mfma_f32_16x16x32_bf16 v[26:29], v[154:157], v[212:215], v[26:29]
	v_mfma_f32_16x16x32_bf16 v[18:21], v[146:149], v[220:223], v[18:21]
	v_mfma_f32_16x16x32_bf16 v[10:13], v[154:157], v[220:223], v[10:13]
	v_mfma_f32_16x16x32_bf16 v[62:65], v[162:165], v[178:181], v[62:65]
	v_mfma_f32_16x16x32_bf16 v[54:57], v[170:173], v[178:181], v[54:57]
	v_mfma_f32_16x16x32_bf16 v[46:49], v[162:165], v[186:189], v[46:49]
	v_mfma_f32_16x16x32_bf16 v[38:41], v[170:173], v[186:189], v[38:41]
	v_mfma_f32_16x16x32_bf16 v[30:33], v[162:165], v[194:197], v[30:33]
	v_mfma_f32_16x16x32_bf16 v[22:25], v[170:173], v[194:197], v[22:25]
	v_mfma_f32_16x16x32_bf16 v[14:17], v[162:165], v[216:219], v[14:17]
	v_mfma_f32_16x16x32_bf16 v[6:9], v[170:173], v[216:219], v[6:9]
	v_mfma_f32_16x16x32_bf16 v[62:65], v[166:169], v[182:185], v[62:65]
	v_mfma_f32_16x16x32_bf16 v[54:57], v[174:177], v[182:185], v[54:57]
	v_mfma_f32_16x16x32_bf16 v[46:49], v[166:169], v[190:193], v[46:49]
	v_mfma_f32_16x16x32_bf16 v[38:41], v[174:177], v[190:193], v[38:41]
	v_mfma_f32_16x16x32_bf16 v[30:33], v[166:169], v[212:215], v[30:33]
	v_mfma_f32_16x16x32_bf16 v[22:25], v[174:177], v[212:215], v[22:25]
	v_mfma_f32_16x16x32_bf16 v[14:17], v[166:169], v[220:223], v[14:17]
	v_mfma_f32_16x16x32_bf16 v[6:9], v[174:177], v[220:223], v[6:9]
	s_setprio 0
	s_barrier
	s_add_i32 s59, s59, 2
	s_add_u32 s26, s26, 0x100
	s_addc_u32 s27, s27, 0
	s_add_u32 s57, s57, 0x100
	s_addc_u32 s58, s58, 0
	s_cmp_gt_u32 s59, 29
	s_cbranch_scc0 .LBB0_137
	s_and_b64 vcc, exec, s[16:17]
	s_cbranch_vccz .LBB0_140
	s_barrier

; #define PG8_STAGE(bufoff, gbase, voff) do { _Pragma("unroll") for (int _i = 0; _i < 2; ++_i) \
;         __builtin_amdgcn_global_load_lds((const unsigned*)((const char*)(gbase) + (voff)[_i]), (LAS unsigned*)(lds + (bufoff) + ldsw + _i * 8192), 16, 0, 0); } while (0)
; #define PG8_LDA(dst, b, h) do { _Pragma("unroll") for (int m = 0; m < 4; ++m) _Pragma("unroll") for (int k = 0; k < 2; ++k) dst[m][k] = *(const LAS bf16x8*)(lds + PG8_SA(b, h) + aoff + m * 2048 + k * 1024); } while (0)
; #define PG8_LDB(dst, b, h) do { _Pragma("unroll") for (int n = 0; n < 2; ++n) _Pragma("unroll") for (int k = 0; k < 2; ++k) dst[n][k] = *(const LAS bf16x8*)(lds + PG8_SB(b, h) + boff + n * 2048 + k * 1024); } while (0)
; #define PG8_MMA(ai, bj, At, Bt) do { __builtin_amdgcn_s_setprio(1); _Pragma("unroll") for (int m = 0; m < 4; ++m) _Pragma("unroll") for (int n = 0; n < 2; ++n) _Pragma("unroll") for (int k = 0; k < 2; ++k) \
;         acc[ai][bj][m][n] = __builtin_amdgcn_mfma_f32_16x16x32_bf16(Bt[n][k], At[m][k], acc[ai][bj][m][n], 0, 0, 0); __builtin_amdgcn_s_setprio(0); } while (0)
; #define PG8_WAIT_V(n) asm volatile("s_waitcnt vmcnt(" #n ")" ::: "memory")
; #define PG8_WAIT_L(n) asm volatile("s_waitcnt lgkmcnt(" #n ")" ::: "memory")
; #define PG8_BAR __builtin_amdgcn_s_barrier()
; template <class Epi, class Sched>
; __device__ __forceinline__ void gemm_phase(LAS unsigned char* lds, const Gemm g, const Sched& S, const Epi& E) {
;     ...
;         for (int t = 0; t < nt; t += 2) {
;             const bool last = (t == nt - 2);
;             const char* a1 = cA + (size_t)(t + 1) * kstep;
;             const char* a2 = last ? nA : cA + (size_t)(t + 2) * kstep; const char* b2 = last ? nB : cB + (size_t)(t + 2) * kstep;
;             const char* a3 = a2 + kstep; const char* b3 = b2 + kstep;
;             if (last && has_next) S.a_ready(nxt);
;             PG8_LDB(B0, 0, 0); PG8_LDB(B1, 0, 1); PG8_SCHED; PG8_LDA(At, 0, 0); PG8_STAGE(PG8_SA(1, 1), a1 + hstepA, voffA);
;             PG8_WAIT_V(8); PG8_WAIT_L(0); PG8_BAR; PG8_MMA(0, 0, At, B0); PG8_MMA(0, 1, At, B1); PG8_BAR; PG8_SCHED;
;             PG8_LDA(At, 0, 1); PG8_STAGE(PG8_SB(0, 0), b2, voffB); PG8_STAGE(PG8_SB(0, 1), b2 + hstepB, voffB); PG8_STAGE(PG8_SA(0, 0), a2, voffA);
;             PG8_WAIT_V(8); PG8_WAIT_L(0); PG8_BAR; PG8_MMA(1, 0, At, B0); PG8_MMA(1, 1, At, B1); PG8_BAR; PG8_SCHED;
.LBB0_281:
	s_add_u32 s26, s20, s24
	s_addc_u32 s27, s21, s25
	s_add_u32 s26, s26, 0x100
	s_addc_u32 s27, s27, 0
	s_add_u32 s63, s60, s24
	s_addc_u32 s65, s61, s25
	s_add_i32 s67, 0, 0x10000
	s_cmpk_eq_i32 s24, 0x2a00
	s_cselect_b32 s29, s5, s27
	s_cselect_b32 s28, s4, s26
	s_cselect_b32 s27, s23, s65
	s_cselect_b32 s26, s22, s63
	s_add_i32 s63, 0, 0x14000
	v_add_u32_e32 v158, s67, v144
	v_add_u32_e32 v174, s63, v144
	ds_read_b128 v[146:149], v158
	ds_read_b128 v[150:153], v158 offset:1024
	ds_read_b128 v[154:157], v158 offset:2048
	ds_read_b128 v[158:161], v158 offset:3072
	ds_read_b128 v[162:165], v174
	ds_read_b128 v[166:169], v174 offset:1024
	ds_read_b128 v[170:173], v174 offset:2048
	ds_read_b128 v[174:177], v174 offset:3072
	v_lshl_add_u64 v[224:225], v[138:139], 0, s[24:25]
	s_add_i32 m0, s50, 0xc000
	ds_read_b128 v[178:181], v145
	ds_read_b128 v[182:185], v145 offset:1024
	ds_read_b128 v[186:189], v145 offset:2048
	ds_read_b128 v[190:193], v145 offset:3072
	ds_read_b128 v[194:197], v145 offset:4096
	ds_read_b128 v[212:215], v145 offset:5120
	ds_read_b128 v[216:219], v145 offset:6144
	ds_read_b128 v[220:223], v145 offset:7168
	global_load_lds_dwordx4 v[224:225], off
	v_lshl_add_u64 v[224:225], v[140:141], 0, s[24:25]
	s_add_i32 m0, s50, 0xe000
	s_nop 0
	global_load_lds_dwordx4 v[224:225], off
	s_waitcnt vmcnt(8)
	s_waitcnt lgkmcnt(0)
	s_barrier
	s_setprio 1
	v_mfma_f32_16x16x32_bf16 v[130:133], v[146:149], v[178:181], v[130:133]
	v_mfma_f32_16x16x32_bf16 v[126:129], v[154:157], v[178:181], v[126:129]
	v_mfma_f32_16x16x32_bf16 v[122:125], v[146:149], v[186:189], v[122:125]
	v_mfma_f32_16x16x32_bf16 v[118:121], v[154:157], v[186:189], v[118:121]
	v_mfma_f32_16x16x32_bf16 v[110:113], v[146:149], v[194:197], v[110:113]
	v_mfma_f32_16x16x32_bf16 v[106:109], v[154:157], v[194:197], v[106:109]
	v_mfma_f32_16x16x32_bf16 v[98:101], v[146:149], v[216:219], v[98:101]
	v_mfma_f32_16x16x32_bf16 v[90:93], v[154:157], v[216:219], v[90:93]
	v_mfma_f32_16x16x32_bf16 v[130:133], v[150:153], v[182:185], v[130:133]
	v_mfma_f32_16x16x32_bf16 v[126:129], v[158:161], v[182:185], v[126:129]
	v_mfma_f32_16x16x32_bf16 v[122:125], v[150:153], v[190:193], v[122:125]
	v_mfma_f32_16x16x32_bf16 v[118:121], v[158:161], v[190:193], v[118:121]
	v_mfma_f32_16x16x32_bf16 v[110:113], v[150:153], v[212:215], v[110:113]
	v_mfma_f32_16x16x32_bf16 v[106:109], v[158:161], v[212:215], v[106:109]
	v_mfma_f32_16x16x32_bf16 v[98:101], v[150:153], v[220:223], v[98:101]
	v_mfma_f32_16x16x32_bf16 v[90:93], v[158:161], v[220:223], v[90:93]
	v_mfma_f32_16x16x32_bf16 v[114:117], v[162:165], v[178:181], v[114:117]
	v_mfma_f32_16x16x32_bf16 v[102:105], v[170:173], v[178:181], v[102:105]
	v_mfma_f32_16x16x32_bf16 v[94:97], v[162:165], v[186:189], v[94:97]
	v_mfma_f32_16x16x32_bf16 v[86:89], v[170:173], v[186:189], v[86:89]
	v_mfma_f32_16x16x32_bf16 v[82:85], v[162:165], v[194:197], v[82:85]
	v_mfma_f32_16x16x32_bf16 v[78:81], v[170:173], v[194:197], v[78:81]
	v_mfma_f32_16x16x32_bf16 v[74:77], v[162:165], v[216:219], v[74:77]
	v_mfma_f32_16x16x32_bf16 v[70:73], v[170:173], v[216:219], v[70:73]
	v_mfma_f32_16x16x32_bf16 v[114:117], v[166:169], v[182:185], v[114:117]
	v_mfma_f32_16x16x32_bf16 v[102:105], v[174:177], v[182:185], v[102:105]
	v_mfma_f32_16x16x32_bf16 v[94:97], v[166:169], v[190:193], v[94:97]
	v_mfma_f32_16x16x32_bf16 v[86:89], v[174:177], v[190:193], v[86:89]
	v_mfma_f32_16x16x32_bf16 v[82:85], v[166:169], v[212:215], v[82:85]
	v_mfma_f32_16x16x32_bf16 v[78:81], v[174:177], v[212:215], v[78:81]
	v_mfma_f32_16x16x32_bf16 v[74:77], v[166:169], v[220:223], v[74:77]
	v_mfma_f32_16x16x32_bf16 v[70:73], v[174:177], v[220:223], v[70:73]
	s_setprio 0
	s_barrier
	s_add_i32 s65, s67, s11
	v_lshl_add_u64 v[224:225], s[26:27], 0, v[4:5]
	s_mov_b32 m0, s65
	ds_read_b128 v[178:181], v145 offset:16384
	ds_read_b128 v[182:185], v145 offset:17408
	ds_read_b128 v[186:189], v145 offset:18432
	ds_read_b128 v[190:193], v145 offset:19456
	ds_read_b128 v[194:197], v145 offset:20480
	ds_read_b128 v[212:215], v145 offset:21504
	ds_read_b128 v[216:219], v145 offset:22528
	ds_read_b128 v[220:223], v145 offset:23552
	global_load_lds_dwordx4 v[224:225], off
	s_add_i32 m0, s65, 0x2000
	s_add_u32 s68, s26, 0x158000
	v_lshl_add_u64 v[226:227], s[26:27], 0, v[2:3]
	s_addc_u32 s69, s27, 0
	s_add_i32 s63, s63, s11
	global_load_lds_dwordx4 v[226:227], off
	v_lshl_add_u64 v[228:229], s[68:69], 0, v[4:5]
	s_mov_b32 m0, s63
	v_lshl_add_u64 v[230:231], s[28:29], 0, v[2:3]
	global_load_lds_dwordx4 v[228:229], off
	v_lshl_add_u64 v[228:229], s[68:69], 0, v[2:3]
	s_add_i32 m0, s63, 0x2000
	s_nop 0
	global_load_lds_dwordx4 v[228:229], off
	v_lshl_add_u64 v[228:229], s[28:29], 0, v[4:5]
	s_mov_b32 m0, s50
	s_nop 0
	global_load_lds_dwordx4 v[228:229], off
	s_mov_b32 m0, s51
	s_nop 0
	global_load_lds_dwordx4 v[230:231], off
	s_waitcnt vmcnt(8)
	s_waitcnt lgkmcnt(0)
	s_barrier
; #define PG8_STAGE(bufoff, gbase, voff) do { _Pragma("unroll") for (int _i = 0; _i < 2; ++_i) \
;         __builtin_amdgcn_global_load_lds((const unsigned*)((const char*)(gbase) + (voff)[_i]), (LAS unsigned*)(lds + (bufoff) + ldsw + _i * 8192), 16, 0, 0); } while (0)
; #define PG8_LDA(dst, b, h) do { _Pragma("unroll") for (int m = 0; m < 4; ++m) _Pragma("unroll") for (int k = 0; k < 2; ++k) dst[m][k] = *(const LAS bf16x8*)(lds + PG8_SA(b, h) + aoff + m * 2048 + k * 1024); } while (0)
; #define PG8_LDB(dst, b, h) do { _Pragma("unroll") for (int n = 0; n < 2; ++n) _Pragma("unroll") for (int k = 0; k < 2; ++k) dst[n][k] = *(const LAS bf16x8*)(lds + PG8_SB(b, h) + boff + n * 2048 + k * 1024); } while (0)
; #define PG8_MMA(ai, bj, At, Bt) do { __builtin_amdgcn_s_setprio(1); _Pragma("unroll") for (int m = 0; m < 4; ++m) _Pragma("unroll") for (int n = 0; n < 2; ++n) _Pragma("unroll") for (int k = 0; k < 2; ++k) \
;         acc[ai][bj][m][n] = __builtin_amdgcn_mfma_f32_16x16x32_bf16(Bt[n][k], At[m][k], acc[ai][bj][m][n], 0, 0, 0); __builtin_amdgcn_s_setprio(0); } while (0)
; #define PG8_WAIT_V(n) asm volatile("s_waitcnt vmcnt(" #n ")" ::: "memory")
; #define PG8_WAIT_L(n) asm volatile("s_waitcnt lgkmcnt(" #n ")" ::: "memory")
; #define PG8_BAR __builtin_amdgcn_s_barrier()
; #define PG8_SCHED __builtin_amdgcn_sched_barrier(0)
; template <class Epi, class Sched>
; __device__ __forceinline__ void gemm_phase(LAS unsigned char* lds, const Gemm g, const Sched& S, const Epi& E) {
;     ...
;             PG8_WAIT_V(8); PG8_WAIT_L(0); PG8_BAR; PG8_MMA(1, 0, At, B0); PG8_MMA(1, 1, At, B1); PG8_BAR; PG8_SCHED;
;             PG8_LDB(B0, 1, 0); PG8_LDB(B1, 1, 1); PG8_SCHED; PG8_LDA(At, 1, 0); PG8_STAGE(PG8_SA(0, 1), a2 + hstepA, voffA);
;             PG8_WAIT_V(8); PG8_WAIT_L(0); PG8_BAR; PG8_MMA(0, 0, At, B0); PG8_MMA(0, 1, At, B1); PG8_BAR; PG8_SCHED;
	s_setprio 1
	v_mfma_f32_16x16x32_bf16 v[66:69], v[146:149], v[178:181], v[66:69]
	v_mfma_f32_16x16x32_bf16 v[62:65], v[154:157], v[178:181], v[62:65]
	v_mfma_f32_16x16x32_bf16 v[58:61], v[146:149], v[186:189], v[58:61]
	v_mfma_f32_16x16x32_bf16 v[54:57], v[154:157], v[186:189], v[54:57]
	v_mfma_f32_16x16x32_bf16 v[50:53], v[146:149], v[194:197], v[50:53]
	v_mfma_f32_16x16x32_bf16 v[42:45], v[154:157], v[194:197], v[42:45]
	v_mfma_f32_16x16x32_bf16 v[34:37], v[146:149], v[216:219], v[34:37]
	v_mfma_f32_16x16x32_bf16 v[26:29], v[154:157], v[216:219], v[26:29]
	v_mfma_f32_16x16x32_bf16 v[66:69], v[150:153], v[182:185], v[66:69]
	v_mfma_f32_16x16x32_bf16 v[62:65], v[158:161], v[182:185], v[62:65]
	v_mfma_f32_16x16x32_bf16 v[58:61], v[150:153], v[190:193], v[58:61]
	v_mfma_f32_16x16x32_bf16 v[54:57], v[158:161], v[190:193], v[54:57]
	v_mfma_f32_16x16x32_bf16 v[50:53], v[150:153], v[212:215], v[50:53]
	v_mfma_f32_16x16x32_bf16 v[42:45], v[158:161], v[212:215], v[42:45]
	v_mfma_f32_16x16x32_bf16 v[34:37], v[150:153], v[220:223], v[34:37]
	v_mfma_f32_16x16x32_bf16 v[26:29], v[158:161], v[220:223], v[26:29]
	v_mfma_f32_16x16x32_bf16 v[46:49], v[162:165], v[178:181], v[46:49]
	v_mfma_f32_16x16x32_bf16 v[38:41], v[170:173], v[178:181], v[38:41]
	v_mfma_f32_16x16x32_bf16 v[30:33], v[162:165], v[186:189], v[30:33]
	v_mfma_f32_16x16x32_bf16 v[22:25], v[170:173], v[186:189], v[22:25]
	v_mfma_f32_16x16x32_bf16 v[18:21], v[162:165], v[194:197], v[18:21]
	v_mfma_f32_16x16x32_bf16 v[14:17], v[170:173], v[194:197], v[14:17]
	v_mfma_f32_16x16x32_bf16 v[10:13], v[162:165], v[216:219], v[10:13]
	v_mfma_f32_16x16x32_bf16 v[6:9], v[170:173], v[216:219], v[6:9]
	v_mfma_f32_16x16x32_bf16 v[46:49], v[166:169], v[182:185], v[46:49]
	v_mfma_f32_16x16x32_bf16 v[38:41], v[174:177], v[182:185], v[38:41]
	v_mfma_f32_16x16x32_bf16 v[30:33], v[166:169], v[190:193], v[30:33]
	v_mfma_f32_16x16x32_bf16 v[22:25], v[174:177], v[190:193], v[22:25]
	v_mfma_f32_16x16x32_bf16 v[18:21], v[166:169], v[212:215], v[18:21]
	v_mfma_f32_16x16x32_bf16 v[14:17], v[174:177], v[212:215], v[14:17]
	v_mfma_f32_16x16x32_bf16 v[10:13], v[166:169], v[220:223], v[10:13]
	v_mfma_f32_16x16x32_bf16 v[6:9], v[174:177], v[220:223], v[6:9]
	s_setprio 0
	s_barrier
	s_add_i32 s63, 0, 0x18000
	s_add_i32 s65, 0, 0x1c000
	v_add_u32_e32 v158, s63, v144
	v_add_u32_e32 v174, s65, v144
	ds_read_b128 v[146:149], v158
	ds_read_b128 v[150:153], v158 offset:1024
	ds_read_b128 v[154:157], v158 offset:2048
	ds_read_b128 v[158:161], v158 offset:3072
	ds_read_b128 v[162:165], v174
	ds_read_b128 v[166:169], v174 offset:1024
	ds_read_b128 v[170:173], v174 offset:2048
	ds_read_b128 v[174:177], v174 offset:3072
	s_add_u32 s28, s28, 0x158000
	s_addc_u32 s29, s29, 0
	s_mov_b32 m0, s52
	v_lshl_add_u64 v[236:237], s[28:29], 0, v[4:5]
	ds_read_b128 v[178:181], v145 offset:32768
	ds_read_b128 v[182:185], v145 offset:33792
	ds_read_b128 v[186:189], v145 offset:34816
	ds_read_b128 v[190:193], v145 offset:35840
	ds_read_b128 v[194:197], v145 offset:36864
	ds_read_b128 v[212:215], v145 offset:37888
	ds_read_b128 v[216:219], v145 offset:38912
	ds_read_b128 v[220:223], v145 offset:39936
	global_load_lds_dwordx4 v[236:237], off
	v_lshl_add_u64 v[236:237], s[28:29], 0, v[2:3]
	s_mov_b32 m0, s53
	s_nop 0
	global_load_lds_dwordx4 v[236:237], off
	s_waitcnt vmcnt(8)
	s_waitcnt lgkmcnt(0)
	s_barrier
	s_setprio 1
	v_mfma_f32_16x16x32_bf16 v[130:133], v[146:149], v[178:181], v[130:133]
	v_mfma_f32_16x16x32_bf16 v[126:129], v[154:157], v[178:181], v[126:129]
	v_mfma_f32_16x16x32_bf16 v[122:125], v[146:149], v[186:189], v[122:125]
	v_mfma_f32_16x16x32_bf16 v[118:121], v[154:157], v[186:189], v[118:121]
	v_mfma_f32_16x16x32_bf16 v[110:113], v[146:149], v[194:197], v[110:113]
	v_mfma_f32_16x16x32_bf16 v[106:109], v[154:157], v[194:197], v[106:109]
	v_mfma_f32_16x16x32_bf16 v[98:101], v[146:149], v[216:219], v[98:101]
	v_mfma_f32_16x16x32_bf16 v[90:93], v[154:157], v[216:219], v[90:93]
	v_mfma_f32_16x16x32_bf16 v[130:133], v[150:153], v[182:185], v[130:133]
	v_mfma_f32_16x16x32_bf16 v[126:129], v[158:161], v[182:185], v[126:129]
	v_mfma_f32_16x16x32_bf16 v[122:125], v[150:153], v[190:193], v[122:125]
	v_mfma_f32_16x16x32_bf16 v[118:121], v[158:161], v[190:193], v[118:121]
	v_mfma_f32_16x16x32_bf16 v[110:113], v[150:153], v[212:215], v[110:113]
	v_mfma_f32_16x16x32_bf16 v[106:109], v[158:161], v[212:215], v[106:109]
	v_mfma_f32_16x16x32_bf16 v[98:101], v[150:153], v[220:223], v[98:101]
	v_mfma_f32_16x16x32_bf16 v[90:93], v[158:161], v[220:223], v[90:93]
	v_mfma_f32_16x16x32_bf16 v[114:117], v[162:165], v[178:181], v[114:117]
	v_mfma_f32_16x16x32_bf16 v[102:105], v[170:173], v[178:181], v[102:105]
	v_mfma_f32_16x16x32_bf16 v[94:97], v[162:165], v[186:189], v[94:97]
	v_mfma_f32_16x16x32_bf16 v[86:89], v[170:173], v[186:189], v[86:89]
	v_mfma_f32_16x16x32_bf16 v[82:85], v[162:165], v[194:197], v[82:85]
	v_mfma_f32_16x16x32_bf16 v[78:81], v[170:173], v[194:197], v[78:81]
	v_mfma_f32_16x16x32_bf16 v[74:77], v[162:165], v[216:219], v[74:77]
	v_mfma_f32_16x16x32_bf16 v[70:73], v[170:173], v[216:219], v[70:73]
	v_mfma_f32_16x16x32_bf16 v[114:117], v[166:169], v[182:185], v[114:117]
	v_mfma_f32_16x16x32_bf16 v[102:105], v[174:177], v[182:185], v[102:105]
	v_mfma_f32_16x16x32_bf16 v[94:97], v[166:169], v[190:193], v[94:97]
	v_mfma_f32_16x16x32_bf16 v[86:89], v[174:177], v[190:193], v[86:89]
	v_mfma_f32_16x16x32_bf16 v[82:85], v[166:169], v[212:215], v[82:85]
	v_mfma_f32_16x16x32_bf16 v[78:81], v[174:177], v[212:215], v[78:81]
	v_mfma_f32_16x16x32_bf16 v[74:77], v[166:169], v[220:223], v[74:77]
	v_mfma_f32_16x16x32_bf16 v[70:73], v[174:177], v[220:223], v[70:73]
	s_setprio 0
	s_barrier
; #define PG8_STAGE(bufoff, gbase, voff) do { _Pragma("unroll") for (int _i = 0; _i < 2; ++_i) \
;         __builtin_amdgcn_global_load_lds((const unsigned*)((const char*)(gbase) + (voff)[_i]), (LAS unsigned*)(lds + (bufoff) + ldsw + _i * 8192), 16, 0, 0); } while (0)
; #define PG8_LDA(dst, b, h) do { _Pragma("unroll") for (int m = 0; m < 4; ++m) _Pragma("unroll") for (int k = 0; k < 2; ++k) dst[m][k] = *(const LAS bf16x8*)(lds + PG8_SA(b, h) + aoff + m * 2048 + k * 1024); } while (0)
; #define PG8_MMA(ai, bj, At, Bt) do { __builtin_amdgcn_s_setprio(1); _Pragma("unroll") for (int m = 0; m < 4; ++m) _Pragma("unroll") for (int n = 0; n < 2; ++n) _Pragma("unroll") for (int k = 0; k < 2; ++k) \
;         acc[ai][bj][m][n] = __builtin_amdgcn_mfma_f32_16x16x32_bf16(Bt[n][k], At[m][k], acc[ai][bj][m][n], 0, 0, 0); __builtin_amdgcn_s_setprio(0); } while (0)
; #define PG8_WAIT_V(n) asm volatile("s_waitcnt vmcnt(" #n ")" ::: "memory")
; #define PG8_WAIT_L(n) asm volatile("s_waitcnt lgkmcnt(" #n ")" ::: "memory")
; #define PG8_BAR __builtin_amdgcn_s_barrier()
; #define PG8_SCHED __builtin_amdgcn_sched_barrier(0)
; template <class Epi, class Sched>
; __device__ __forceinline__ void gemm_phase(LAS unsigned char* lds, const Gemm g, const Sched& S, const Epi& E) {
;     ...
;             PG8_LDA(At, 1, 1); PG8_STAGE(PG8_SB(1, 0), b3, voffB); PG8_STAGE(PG8_SB(1, 1), b3 + hstepB, voffB); PG8_STAGE(PG8_SA(1, 0), a3, voffA);
;             PG8_WAIT_V(8); PG8_WAIT_L(0); PG8_BAR; PG8_MMA(1, 0, At, B0); PG8_MMA(1, 1, At, B1); PG8_BAR; PG8_SCHED;
;         }
;         if (wr == 0) PG8_BAR;
	s_add_i32 s28, s63, s11
	v_lshl_add_u64 v[224:225], v[224:225], 0, s[36:37]
	s_mov_b32 m0, s28
	ds_read_b128 v[178:181], v145 offset:49152
	ds_read_b128 v[182:185], v145 offset:50176
	ds_read_b128 v[186:189], v145 offset:51200
	ds_read_b128 v[190:193], v145 offset:52224
	ds_read_b128 v[194:197], v145 offset:53248
	ds_read_b128 v[212:215], v145 offset:54272
	ds_read_b128 v[216:219], v145 offset:55296
	ds_read_b128 v[220:223], v145 offset:56320
	global_load_lds_dwordx4 v[224:225], off
	s_add_i32 m0, s28, 0x2000
	s_add_u32 s26, s26, 0x158080
	v_lshl_add_u64 v[224:225], v[226:227], 0, s[36:37]
	s_addc_u32 s27, s27, 0
	s_add_i32 s28, s65, s11
	global_load_lds_dwordx4 v[224:225], off
	v_lshl_add_u64 v[224:225], s[26:27], 0, v[4:5]
	s_mov_b32 m0, s28
	s_nop 0
	global_load_lds_dwordx4 v[224:225], off
	v_lshl_add_u64 v[224:225], s[26:27], 0, v[2:3]
	s_add_i32 m0, s28, 0x2000
	s_nop 0
	global_load_lds_dwordx4 v[224:225], off
	v_lshl_add_u64 v[224:225], v[228:229], 0, s[36:37]
	s_mov_b32 m0, s54
	s_nop 0
	global_load_lds_dwordx4 v[224:225], off
	v_lshl_add_u64 v[224:225], v[230:231], 0, s[36:37]
	s_mov_b32 m0, s55
	s_nop 0
	global_load_lds_dwordx4 v[224:225], off
	s_waitcnt vmcnt(8)
	s_waitcnt lgkmcnt(0)
	s_barrier
	s_setprio 1
	v_mfma_f32_16x16x32_bf16 v[66:69], v[146:149], v[178:181], v[66:69]
	v_mfma_f32_16x16x32_bf16 v[62:65], v[154:157], v[178:181], v[62:65]
	v_mfma_f32_16x16x32_bf16 v[58:61], v[146:149], v[186:189], v[58:61]
	v_mfma_f32_16x16x32_bf16 v[54:57], v[154:157], v[186:189], v[54:57]
	v_mfma_f32_16x16x32_bf16 v[50:53], v[146:149], v[194:197], v[50:53]
	v_mfma_f32_16x16x32_bf16 v[42:45], v[154:157], v[194:197], v[42:45]
	v_mfma_f32_16x16x32_bf16 v[34:37], v[146:149], v[216:219], v[34:37]
	v_mfma_f32_16x16x32_bf16 v[26:29], v[154:157], v[216:219], v[26:29]
	v_mfma_f32_16x16x32_bf16 v[66:69], v[150:153], v[182:185], v[66:69]
	v_mfma_f32_16x16x32_bf16 v[62:65], v[158:161], v[182:185], v[62:65]
	v_mfma_f32_16x16x32_bf16 v[58:61], v[150:153], v[190:193], v[58:61]
	v_mfma_f32_16x16x32_bf16 v[54:57], v[158:161], v[190:193], v[54:57]
	v_mfma_f32_16x16x32_bf16 v[50:53], v[150:153], v[212:215], v[50:53]
	v_mfma_f32_16x16x32_bf16 v[42:45], v[158:161], v[212:215], v[42:45]
	v_mfma_f32_16x16x32_bf16 v[34:37], v[150:153], v[220:223], v[34:37]
	v_mfma_f32_16x16x32_bf16 v[26:29], v[158:161], v[220:223], v[26:29]
	v_mfma_f32_16x16x32_bf16 v[46:49], v[162:165], v[178:181], v[46:49]
	v_mfma_f32_16x16x32_bf16 v[38:41], v[170:173], v[178:181], v[38:41]
	v_mfma_f32_16x16x32_bf16 v[30:33], v[162:165], v[186:189], v[30:33]
	v_mfma_f32_16x16x32_bf16 v[22:25], v[170:173], v[186:189], v[22:25]
	v_mfma_f32_16x16x32_bf16 v[18:21], v[162:165], v[194:197], v[18:21]
	v_mfma_f32_16x16x32_bf16 v[14:17], v[170:173], v[194:197], v[14:17]
	v_mfma_f32_16x16x32_bf16 v[10:13], v[162:165], v[216:219], v[10:13]
	v_mfma_f32_16x16x32_bf16 v[6:9], v[170:173], v[216:219], v[6:9]
	v_mfma_f32_16x16x32_bf16 v[46:49], v[166:169], v[182:185], v[46:49]
	v_mfma_f32_16x16x32_bf16 v[38:41], v[174:177], v[182:185], v[38:41]
	v_mfma_f32_16x16x32_bf16 v[30:33], v[166:169], v[190:193], v[30:33]
	v_mfma_f32_16x16x32_bf16 v[22:25], v[174:177], v[190:193], v[22:25]
	v_mfma_f32_16x16x32_bf16 v[18:21], v[166:169], v[212:215], v[18:21]
	v_mfma_f32_16x16x32_bf16 v[14:17], v[174:177], v[212:215], v[14:17]
	v_mfma_f32_16x16x32_bf16 v[10:13], v[166:169], v[220:223], v[10:13]
	v_mfma_f32_16x16x32_bf16 v[6:9], v[174:177], v[220:223], v[6:9]
	s_setprio 0
	s_barrier
	s_add_i32 s62, s62, 2
	s_add_u32 s24, s24, 0x100
	s_addc_u32 s25, s25, 0
	s_cmpk_gt_u32 s62, 0x53
	s_cbranch_scc0 .LBB0_281
	s_and_b64 vcc, exec, s[18:19]
	s_cbranch_vccz .LBB0_284
	s_barrier

; #define PG8_STAGE(bufoff, gbase, voff) do { _Pragma("unroll") for (int _i = 0; _i < 2; ++_i) \
;         __builtin_amdgcn_global_load_lds((const unsigned*)((const char*)(gbase) + (voff)[_i]), (LAS unsigned*)(lds + (bufoff) + ldsw + _i * 8192), 16, 0, 0); } while (0)
; #define PG8_LDA(dst, b, h) do { _Pragma("unroll") for (int m = 0; m < 4; ++m) _Pragma("unroll") for (int k = 0; k < 2; ++k) dst[m][k] = *(const LAS bf16x8*)(lds + PG8_SA(b, h) + aoff + m * 2048 + k * 1024); } while (0)
; #define PG8_LDB(dst, b, h) do { _Pragma("unroll") for (int n = 0; n < 2; ++n) _Pragma("unroll") for (int k = 0; k < 2; ++k) dst[n][k] = *(const LAS bf16x8*)(lds + PG8_SB(b, h) + boff + n * 2048 + k * 1024); } while (0)
; #define PG8_MMA(ai, bj, At, Bt) do { __builtin_amdgcn_s_setprio(1); _Pragma("unroll") for (int m = 0; m < 4; ++m) _Pragma("unroll") for (int n = 0; n < 2; ++n) _Pragma("unroll") for (int k = 0; k < 2; ++k) \
;         acc[ai][bj][m][n] = __builtin_amdgcn_mfma_f32_16x16x32_bf16(Bt[n][k], At[m][k], acc[ai][bj][m][n], 0, 0, 0); __builtin_amdgcn_s_setprio(0); } while (0)
; #define PG8_WAIT_V(n) asm volatile("s_waitcnt vmcnt(" #n ")" ::: "memory")
; #define PG8_WAIT_L(n) asm volatile("s_waitcnt lgkmcnt(" #n ")" ::: "memory")
; #define PG8_BAR __builtin_amdgcn_s_barrier()
; template <class Epi, class Sched>
; __device__ __forceinline__ void gemm_phase(LAS unsigned char* lds, const Gemm g, const Sched& S, const Epi& E) {
;     ...
;         for (int t = 0; t < nt; t += 2) {
;             const bool last = (t == nt - 2);
;             const char* a1 = cA + (size_t)(t + 1) * kstep;
;             const char* a2 = last ? nA : cA + (size_t)(t + 2) * kstep; const char* b2 = last ? nB : cB + (size_t)(t + 2) * kstep;
;             const char* a3 = a2 + kstep; const char* b3 = b2 + kstep;
;             if (last && has_next) S.a_ready(nxt);
;             PG8_LDB(B0, 0, 0); PG8_LDB(B1, 0, 1); PG8_SCHED; PG8_LDA(At, 0, 0); PG8_STAGE(PG8_SA(1, 1), a1 + hstepA, voffA);
;             PG8_WAIT_V(8); PG8_WAIT_L(0); PG8_BAR; PG8_MMA(0, 0, At, B0); PG8_MMA(0, 1, At, B1); PG8_BAR; PG8_SCHED;
;             PG8_LDA(At, 0, 1); PG8_STAGE(PG8_SB(0, 0), b2, voffB); PG8_STAGE(PG8_SB(0, 1), b2 + hstepB, voffB); PG8_STAGE(PG8_SA(0, 0), a2, voffA);
;             PG8_WAIT_V(8); PG8_WAIT_L(0); PG8_BAR; PG8_MMA(1, 0, At, B0); PG8_MMA(1, 1, At, B1); PG8_BAR; PG8_SCHED;
.LBB0_513:
	s_add_u32 s42, s38, 0xfff80080
	s_addc_u32 s43, s39, -1
	s_add_i32 s61, 0, 0x10000
	s_cmp_eq_u32 s60, 28
	s_cselect_b32 s45, s21, s43
	s_cselect_b32 s44, s27, s42
	s_cselect_b32 s43, s19, s59
	s_cselect_b32 s42, s29, s58
	s_add_i32 s64, 0, 0x14000
	v_add_u32_e32 v98, s61, v236
	v_add_u32_e32 v162, s64, v236
	ds_read_b128 v[86:89], v98
	ds_read_b128 v[90:93], v98 offset:1024
	ds_read_b128 v[94:97], v98 offset:2048
	ds_read_b128 v[98:101], v98 offset:3072
	ds_read_b128 v[150:153], v162
	ds_read_b128 v[154:157], v162 offset:1024
	ds_read_b128 v[158:161], v162 offset:2048
	ds_read_b128 v[162:165], v162 offset:3072
	v_lshl_add_u64 v[228:229], s[38:39], 0, v[224:225]
	s_add_i32 m0, s50, 0xc000
	ds_read_b128 v[166:169], v237
	ds_read_b128 v[170:173], v237 offset:1024
	ds_read_b128 v[174:177], v237 offset:2048
	ds_read_b128 v[178:181], v237 offset:3072
	ds_read_b128 v[182:185], v237 offset:4096
	ds_read_b128 v[186:189], v237 offset:5120
	ds_read_b128 v[190:193], v237 offset:6144
	ds_read_b128 v[194:197], v237 offset:7168
	global_load_lds_dwordx4 v[228:229], off
	v_lshl_add_u64 v[228:229], s[38:39], 0, v[226:227]
	s_add_i32 m0, s50, 0xe000
	s_nop 0
	global_load_lds_dwordx4 v[228:229], off
	s_waitcnt vmcnt(8)
	s_waitcnt lgkmcnt(0)
	s_barrier
	s_setprio 1
	v_mfma_f32_16x16x32_bf16 v[146:149], v[86:89], v[166:169], v[146:149]
	v_mfma_f32_16x16x32_bf16 v[142:145], v[94:97], v[166:169], v[142:145]
	v_mfma_f32_16x16x32_bf16 v[130:133], v[86:89], v[174:177], v[130:133]
	v_mfma_f32_16x16x32_bf16 v[126:129], v[94:97], v[174:177], v[126:129]
	v_mfma_f32_16x16x32_bf16 v[114:117], v[86:89], v[182:185], v[114:117]
	v_mfma_f32_16x16x32_bf16 v[110:113], v[94:97], v[182:185], v[110:113]
	v_mfma_f32_16x16x32_bf16 v[82:85], v[86:89], v[190:193], v[82:85]
	v_mfma_f32_16x16x32_bf16 v[78:81], v[94:97], v[190:193], v[78:81]
	v_mfma_f32_16x16x32_bf16 v[146:149], v[90:93], v[170:173], v[146:149]
	v_mfma_f32_16x16x32_bf16 v[142:145], v[98:101], v[170:173], v[142:145]
	v_mfma_f32_16x16x32_bf16 v[130:133], v[90:93], v[178:181], v[130:133]
	v_mfma_f32_16x16x32_bf16 v[126:129], v[98:101], v[178:181], v[126:129]
	v_mfma_f32_16x16x32_bf16 v[114:117], v[90:93], v[186:189], v[114:117]
	v_mfma_f32_16x16x32_bf16 v[110:113], v[98:101], v[186:189], v[110:113]
	v_mfma_f32_16x16x32_bf16 v[82:85], v[90:93], v[194:197], v[82:85]
	v_mfma_f32_16x16x32_bf16 v[78:81], v[98:101], v[194:197], v[78:81]
	v_mfma_f32_16x16x32_bf16 v[138:141], v[150:153], v[166:169], v[138:141]
	v_mfma_f32_16x16x32_bf16 v[134:137], v[158:161], v[166:169], v[134:137]
	v_mfma_f32_16x16x32_bf16 v[122:125], v[150:153], v[174:177], v[122:125]
	v_mfma_f32_16x16x32_bf16 v[118:121], v[158:161], v[174:177], v[118:121]
	v_mfma_f32_16x16x32_bf16 v[106:109], v[150:153], v[182:185], v[106:109]
	v_mfma_f32_16x16x32_bf16 v[102:105], v[158:161], v[182:185], v[102:105]
	v_mfma_f32_16x16x32_bf16 v[74:77], v[150:153], v[190:193], v[74:77]
	v_mfma_f32_16x16x32_bf16 v[70:73], v[158:161], v[190:193], v[70:73]
	v_mfma_f32_16x16x32_bf16 v[138:141], v[154:157], v[170:173], v[138:141]
	v_mfma_f32_16x16x32_bf16 v[134:137], v[162:165], v[170:173], v[134:137]
	v_mfma_f32_16x16x32_bf16 v[122:125], v[154:157], v[178:181], v[122:125]
	v_mfma_f32_16x16x32_bf16 v[118:121], v[162:165], v[178:181], v[118:121]
	v_mfma_f32_16x16x32_bf16 v[106:109], v[154:157], v[186:189], v[106:109]
	v_mfma_f32_16x16x32_bf16 v[102:105], v[162:165], v[186:189], v[102:105]
	v_mfma_f32_16x16x32_bf16 v[74:77], v[154:157], v[194:197], v[74:77]
	v_mfma_f32_16x16x32_bf16 v[70:73], v[162:165], v[194:197], v[70:73]
	s_setprio 0
	s_barrier
	s_add_i32 s61, s61, s49
	v_lshl_add_u64 v[228:229], s[42:43], 0, v[212:213]
	s_mov_b32 m0, s61
	ds_read_b128 v[166:169], v237 offset:16384
	ds_read_b128 v[170:173], v237 offset:17408
	ds_read_b128 v[174:177], v237 offset:18432
	ds_read_b128 v[178:181], v237 offset:19456
	ds_read_b128 v[182:185], v237 offset:20480
	ds_read_b128 v[186:189], v237 offset:21504
	ds_read_b128 v[190:193], v237 offset:22528
	ds_read_b128 v[194:197], v237 offset:23552
	global_load_lds_dwordx4 v[228:229], off
	s_add_i32 m0, s61, 0x2000
	s_add_u32 s62, s42, 0x80000
	v_lshl_add_u64 v[230:231], s[42:43], 0, v[216:217]
	s_addc_u32 s63, s43, 0
	s_add_i32 s61, s64, s49
	global_load_lds_dwordx4 v[230:231], off
	v_lshl_add_u64 v[238:239], s[62:63], 0, v[212:213]
	s_mov_b32 m0, s61
	v_lshl_add_u64 v[240:241], s[44:45], 0, v[214:215]
	global_load_lds_dwordx4 v[238:239], off
	v_lshl_add_u64 v[238:239], s[62:63], 0, v[216:217]
	s_add_i32 m0, s61, 0x2000
	s_nop 0
	global_load_lds_dwordx4 v[238:239], off
	v_lshl_add_u64 v[238:239], s[44:45], 0, v[2:3]
	s_mov_b32 m0, s50
	s_nop 0
	global_load_lds_dwordx4 v[238:239], off
	s_mov_b32 m0, s51
	s_nop 0
	global_load_lds_dwordx4 v[240:241], off
	s_waitcnt vmcnt(8)
	s_waitcnt lgkmcnt(0)
	s_barrier
; #define PG8_STAGE(bufoff, gbase, voff) do { _Pragma("unroll") for (int _i = 0; _i < 2; ++_i) \
;         __builtin_amdgcn_global_load_lds((const unsigned*)((const char*)(gbase) + (voff)[_i]), (LAS unsigned*)(lds + (bufoff) + ldsw + _i * 8192), 16, 0, 0); } while (0)
; #define PG8_LDA(dst, b, h) do { _Pragma("unroll") for (int m = 0; m < 4; ++m) _Pragma("unroll") for (int k = 0; k < 2; ++k) dst[m][k] = *(const LAS bf16x8*)(lds + PG8_SA(b, h) + aoff + m * 2048 + k * 1024); } while (0)
; #define PG8_LDB(dst, b, h) do { _Pragma("unroll") for (int n = 0; n < 2; ++n) _Pragma("unroll") for (int k = 0; k < 2; ++k) dst[n][k] = *(const LAS bf16x8*)(lds + PG8_SB(b, h) + boff + n * 2048 + k * 1024); } while (0)
; #define PG8_MMA(ai, bj, At, Bt) do { __builtin_amdgcn_s_setprio(1); _Pragma("unroll") for (int m = 0; m < 4; ++m) _Pragma("unroll") for (int n = 0; n < 2; ++n) _Pragma("unroll") for (int k = 0; k < 2; ++k) \
;         acc[ai][bj][m][n] = __builtin_amdgcn_mfma_f32_16x16x32_bf16(Bt[n][k], At[m][k], acc[ai][bj][m][n], 0, 0, 0); __builtin_amdgcn_s_setprio(0); } while (0)
; #define PG8_WAIT_V(n) asm volatile("s_waitcnt vmcnt(" #n ")" ::: "memory")
; #define PG8_WAIT_L(n) asm volatile("s_waitcnt lgkmcnt(" #n ")" ::: "memory")
; #define PG8_BAR __builtin_amdgcn_s_barrier()
; #define PG8_SCHED __builtin_amdgcn_sched_barrier(0)
; template <class Epi, class Sched>
; __device__ __forceinline__ void gemm_phase(LAS unsigned char* lds, const Gemm g, const Sched& S, const Epi& E) {
;     ...
;             PG8_WAIT_V(8); PG8_WAIT_L(0); PG8_BAR; PG8_MMA(1, 0, At, B0); PG8_MMA(1, 1, At, B1); PG8_BAR; PG8_SCHED;
;             PG8_LDB(B0, 1, 0); PG8_LDB(B1, 1, 1); PG8_SCHED; PG8_LDA(At, 1, 0); PG8_STAGE(PG8_SA(0, 1), a2 + hstepA, voffA);
;             PG8_WAIT_V(8); PG8_WAIT_L(0); PG8_BAR; PG8_MMA(0, 0, At, B0); PG8_MMA(0, 1, At, B1); PG8_BAR; PG8_SCHED;
	s_setprio 1
	v_mfma_f32_16x16x32_bf16 v[66:69], v[86:89], v[166:169], v[66:69]
	v_mfma_f32_16x16x32_bf16 v[62:65], v[94:97], v[166:169], v[62:65]
	v_mfma_f32_16x16x32_bf16 v[50:53], v[86:89], v[174:177], v[50:53]
	v_mfma_f32_16x16x32_bf16 v[46:49], v[94:97], v[174:177], v[46:49]
	v_mfma_f32_16x16x32_bf16 v[34:37], v[86:89], v[182:185], v[34:37]
	v_mfma_f32_16x16x32_bf16 v[30:33], v[94:97], v[182:185], v[30:33]
	v_mfma_f32_16x16x32_bf16 v[18:21], v[86:89], v[190:193], v[18:21]
	v_mfma_f32_16x16x32_bf16 v[14:17], v[94:97], v[190:193], v[14:17]
	v_mfma_f32_16x16x32_bf16 v[66:69], v[90:93], v[170:173], v[66:69]
	v_mfma_f32_16x16x32_bf16 v[62:65], v[98:101], v[170:173], v[62:65]
	v_mfma_f32_16x16x32_bf16 v[50:53], v[90:93], v[178:181], v[50:53]
	v_mfma_f32_16x16x32_bf16 v[46:49], v[98:101], v[178:181], v[46:49]
	v_mfma_f32_16x16x32_bf16 v[34:37], v[90:93], v[186:189], v[34:37]
	v_mfma_f32_16x16x32_bf16 v[30:33], v[98:101], v[186:189], v[30:33]
	v_mfma_f32_16x16x32_bf16 v[18:21], v[90:93], v[194:197], v[18:21]
	v_mfma_f32_16x16x32_bf16 v[14:17], v[98:101], v[194:197], v[14:17]
	v_mfma_f32_16x16x32_bf16 v[58:61], v[150:153], v[166:169], v[58:61]
	v_mfma_f32_16x16x32_bf16 v[54:57], v[158:161], v[166:169], v[54:57]
	v_mfma_f32_16x16x32_bf16 v[42:45], v[150:153], v[174:177], v[42:45]
	v_mfma_f32_16x16x32_bf16 v[38:41], v[158:161], v[174:177], v[38:41]
	v_mfma_f32_16x16x32_bf16 v[26:29], v[150:153], v[182:185], v[26:29]
	v_mfma_f32_16x16x32_bf16 v[22:25], v[158:161], v[182:185], v[22:25]
	v_mfma_f32_16x16x32_bf16 v[10:13], v[150:153], v[190:193], v[10:13]
	v_mfma_f32_16x16x32_bf16 v[6:9], v[158:161], v[190:193], v[6:9]
	v_mfma_f32_16x16x32_bf16 v[58:61], v[154:157], v[170:173], v[58:61]
	v_mfma_f32_16x16x32_bf16 v[54:57], v[162:165], v[170:173], v[54:57]
	v_mfma_f32_16x16x32_bf16 v[42:45], v[154:157], v[178:181], v[42:45]
	v_mfma_f32_16x16x32_bf16 v[38:41], v[162:165], v[178:181], v[38:41]
	v_mfma_f32_16x16x32_bf16 v[26:29], v[154:157], v[186:189], v[26:29]
	v_mfma_f32_16x16x32_bf16 v[22:25], v[162:165], v[186:189], v[22:25]
	v_mfma_f32_16x16x32_bf16 v[10:13], v[154:157], v[194:197], v[10:13]
	v_mfma_f32_16x16x32_bf16 v[6:9], v[162:165], v[194:197], v[6:9]
	s_setprio 0
	s_barrier
	s_add_i32 s61, 0, 0x18000
	s_add_i32 s62, 0, 0x1c000
	v_add_u32_e32 v98, s61, v236
	v_add_u32_e32 v162, s62, v236
	ds_read_b128 v[86:89], v98
	ds_read_b128 v[90:93], v98 offset:1024
	ds_read_b128 v[94:97], v98 offset:2048
	ds_read_b128 v[98:101], v98 offset:3072
	ds_read_b128 v[150:153], v162
	ds_read_b128 v[154:157], v162 offset:1024
	ds_read_b128 v[158:161], v162 offset:2048
	ds_read_b128 v[162:165], v162 offset:3072
	s_add_u32 s44, s44, 0x80000
	s_addc_u32 s45, s45, 0
	s_mov_b32 m0, s52
	v_lshl_add_u64 v[242:243], s[44:45], 0, v[2:3]
	ds_read_b128 v[166:169], v237 offset:32768
	ds_read_b128 v[170:173], v237 offset:33792
	ds_read_b128 v[174:177], v237 offset:34816
	ds_read_b128 v[178:181], v237 offset:35840
	ds_read_b128 v[182:185], v237 offset:36864
	ds_read_b128 v[186:189], v237 offset:37888
	ds_read_b128 v[190:193], v237 offset:38912
	ds_read_b128 v[194:197], v237 offset:39936
	global_load_lds_dwordx4 v[242:243], off
	v_lshl_add_u64 v[242:243], s[44:45], 0, v[214:215]
	s_mov_b32 m0, s53
	s_nop 0
	global_load_lds_dwordx4 v[242:243], off
	s_waitcnt vmcnt(8)
	s_waitcnt lgkmcnt(0)
	s_barrier
	s_setprio 1
	v_mfma_f32_16x16x32_bf16 v[146:149], v[86:89], v[166:169], v[146:149]
	v_mfma_f32_16x16x32_bf16 v[142:145], v[94:97], v[166:169], v[142:145]
	v_mfma_f32_16x16x32_bf16 v[130:133], v[86:89], v[174:177], v[130:133]
	v_mfma_f32_16x16x32_bf16 v[126:129], v[94:97], v[174:177], v[126:129]
	v_mfma_f32_16x16x32_bf16 v[114:117], v[86:89], v[182:185], v[114:117]
	v_mfma_f32_16x16x32_bf16 v[110:113], v[94:97], v[182:185], v[110:113]
	v_mfma_f32_16x16x32_bf16 v[82:85], v[86:89], v[190:193], v[82:85]
	v_mfma_f32_16x16x32_bf16 v[78:81], v[94:97], v[190:193], v[78:81]
	v_mfma_f32_16x16x32_bf16 v[146:149], v[90:93], v[170:173], v[146:149]
	v_mfma_f32_16x16x32_bf16 v[142:145], v[98:101], v[170:173], v[142:145]
	v_mfma_f32_16x16x32_bf16 v[130:133], v[90:93], v[178:181], v[130:133]
	v_mfma_f32_16x16x32_bf16 v[126:129], v[98:101], v[178:181], v[126:129]
	v_mfma_f32_16x16x32_bf16 v[114:117], v[90:93], v[186:189], v[114:117]
	v_mfma_f32_16x16x32_bf16 v[110:113], v[98:101], v[186:189], v[110:113]
	v_mfma_f32_16x16x32_bf16 v[82:85], v[90:93], v[194:197], v[82:85]
	v_mfma_f32_16x16x32_bf16 v[78:81], v[98:101], v[194:197], v[78:81]
	v_mfma_f32_16x16x32_bf16 v[138:141], v[150:153], v[166:169], v[138:141]
	v_mfma_f32_16x16x32_bf16 v[134:137], v[158:161], v[166:169], v[134:137]
	v_mfma_f32_16x16x32_bf16 v[122:125], v[150:153], v[174:177], v[122:125]
	v_mfma_f32_16x16x32_bf16 v[118:121], v[158:161], v[174:177], v[118:121]
	v_mfma_f32_16x16x32_bf16 v[106:109], v[150:153], v[182:185], v[106:109]
	v_mfma_f32_16x16x32_bf16 v[102:105], v[158:161], v[182:185], v[102:105]
	v_mfma_f32_16x16x32_bf16 v[74:77], v[150:153], v[190:193], v[74:77]
	v_mfma_f32_16x16x32_bf16 v[70:73], v[158:161], v[190:193], v[70:73]
	v_mfma_f32_16x16x32_bf16 v[138:141], v[154:157], v[170:173], v[138:141]
	v_mfma_f32_16x16x32_bf16 v[134:137], v[162:165], v[170:173], v[134:137]
	v_mfma_f32_16x16x32_bf16 v[122:125], v[154:157], v[178:181], v[122:125]
	v_mfma_f32_16x16x32_bf16 v[118:121], v[162:165], v[178:181], v[118:121]
	v_mfma_f32_16x16x32_bf16 v[106:109], v[154:157], v[186:189], v[106:109]
	v_mfma_f32_16x16x32_bf16 v[102:105], v[162:165], v[186:189], v[102:105]
	v_mfma_f32_16x16x32_bf16 v[74:77], v[154:157], v[194:197], v[74:77]
	v_mfma_f32_16x16x32_bf16 v[70:73], v[162:165], v[194:197], v[70:73]
	s_setprio 0
	s_barrier
; #define PG8_STAGE(bufoff, gbase, voff) do { _Pragma("unroll") for (int _i = 0; _i < 2; ++_i) \
;         __builtin_amdgcn_global_load_lds((const unsigned*)((const char*)(gbase) + (voff)[_i]), (LAS unsigned*)(lds + (bufoff) + ldsw + _i * 8192), 16, 0, 0); } while (0)
; #define PG8_LDA(dst, b, h) do { _Pragma("unroll") for (int m = 0; m < 4; ++m) _Pragma("unroll") for (int k = 0; k < 2; ++k) dst[m][k] = *(const LAS bf16x8*)(lds + PG8_SA(b, h) + aoff + m * 2048 + k * 1024); } while (0)
; #define PG8_MMA(ai, bj, At, Bt) do { __builtin_amdgcn_s_setprio(1); _Pragma("unroll") for (int m = 0; m < 4; ++m) _Pragma("unroll") for (int n = 0; n < 2; ++n) _Pragma("unroll") for (int k = 0; k < 2; ++k) \
;         acc[ai][bj][m][n] = __builtin_amdgcn_mfma_f32_16x16x32_bf16(Bt[n][k], At[m][k], acc[ai][bj][m][n], 0, 0, 0); __builtin_amdgcn_s_setprio(0); } while (0)
; #define PG8_WAIT_V(n) asm volatile("s_waitcnt vmcnt(" #n ")" ::: "memory")
; #define PG8_WAIT_L(n) asm volatile("s_waitcnt lgkmcnt(" #n ")" ::: "memory")
; #define PG8_BAR __builtin_amdgcn_s_barrier()
; #define PG8_SCHED __builtin_amdgcn_sched_barrier(0)
; template <class Epi, class Sched>
; __device__ __forceinline__ void gemm_phase(LAS unsigned char* lds, const Gemm g, const Sched& S, const Epi& E) {
;     ...
;             PG8_LDA(At, 1, 1); PG8_STAGE(PG8_SB(1, 0), b3, voffB); PG8_STAGE(PG8_SB(1, 1), b3 + hstepB, voffB); PG8_STAGE(PG8_SA(1, 0), a3, voffA);
;             PG8_WAIT_V(8); PG8_WAIT_L(0); PG8_BAR; PG8_MMA(1, 0, At, B0); PG8_MMA(1, 1, At, B1); PG8_BAR; PG8_SCHED;
;         }
;         if (wr == 0) PG8_BAR;
	s_add_i32 s44, s61, s49
	v_lshl_add_u64 v[228:229], v[228:229], 0, s[36:37]
	s_mov_b32 m0, s44
	ds_read_b128 v[166:169], v237 offset:49152
	ds_read_b128 v[170:173], v237 offset:50176
	ds_read_b128 v[174:177], v237 offset:51200
	ds_read_b128 v[178:181], v237 offset:52224
	ds_read_b128 v[182:185], v237 offset:53248
	ds_read_b128 v[186:189], v237 offset:54272
	ds_read_b128 v[190:193], v237 offset:55296
	ds_read_b128 v[194:197], v237 offset:56320
	global_load_lds_dwordx4 v[228:229], off
	s_add_i32 m0, s44, 0x2000
	s_add_u32 s42, s42, 0x80080
	v_lshl_add_u64 v[228:229], v[230:231], 0, s[36:37]
	s_addc_u32 s43, s43, 0
	s_add_i32 s44, s62, s49
	global_load_lds_dwordx4 v[228:229], off
	v_lshl_add_u64 v[228:229], s[42:43], 0, v[212:213]
	s_mov_b32 m0, s44
	s_nop 0
	global_load_lds_dwordx4 v[228:229], off
	v_lshl_add_u64 v[228:229], s[42:43], 0, v[216:217]
	s_add_i32 m0, s44, 0x2000
	s_nop 0
	global_load_lds_dwordx4 v[228:229], off
	v_lshl_add_u64 v[228:229], v[238:239], 0, s[36:37]
	s_mov_b32 m0, s54
	s_nop 0
	global_load_lds_dwordx4 v[228:229], off
	v_lshl_add_u64 v[228:229], v[240:241], 0, s[36:37]
	s_mov_b32 m0, s55
	s_nop 0
	global_load_lds_dwordx4 v[228:229], off
	s_waitcnt vmcnt(8)
	s_waitcnt lgkmcnt(0)
	s_barrier
	s_setprio 1
	v_mfma_f32_16x16x32_bf16 v[66:69], v[86:89], v[166:169], v[66:69]
	v_mfma_f32_16x16x32_bf16 v[62:65], v[94:97], v[166:169], v[62:65]
	v_mfma_f32_16x16x32_bf16 v[50:53], v[86:89], v[174:177], v[50:53]
	v_mfma_f32_16x16x32_bf16 v[46:49], v[94:97], v[174:177], v[46:49]
	v_mfma_f32_16x16x32_bf16 v[34:37], v[86:89], v[182:185], v[34:37]
	v_mfma_f32_16x16x32_bf16 v[30:33], v[94:97], v[182:185], v[30:33]
	v_mfma_f32_16x16x32_bf16 v[18:21], v[86:89], v[190:193], v[18:21]
	v_mfma_f32_16x16x32_bf16 v[14:17], v[94:97], v[190:193], v[14:17]
	v_mfma_f32_16x16x32_bf16 v[66:69], v[90:93], v[170:173], v[66:69]
	v_mfma_f32_16x16x32_bf16 v[62:65], v[98:101], v[170:173], v[62:65]
	v_mfma_f32_16x16x32_bf16 v[50:53], v[90:93], v[178:181], v[50:53]
	v_mfma_f32_16x16x32_bf16 v[46:49], v[98:101], v[178:181], v[46:49]
	v_mfma_f32_16x16x32_bf16 v[34:37], v[90:93], v[186:189], v[34:37]
	v_mfma_f32_16x16x32_bf16 v[30:33], v[98:101], v[186:189], v[30:33]
	v_mfma_f32_16x16x32_bf16 v[18:21], v[90:93], v[194:197], v[18:21]
	v_mfma_f32_16x16x32_bf16 v[14:17], v[98:101], v[194:197], v[14:17]
	v_mfma_f32_16x16x32_bf16 v[58:61], v[150:153], v[166:169], v[58:61]
	v_mfma_f32_16x16x32_bf16 v[54:57], v[158:161], v[166:169], v[54:57]
	v_mfma_f32_16x16x32_bf16 v[42:45], v[150:153], v[174:177], v[42:45]
	v_mfma_f32_16x16x32_bf16 v[38:41], v[158:161], v[174:177], v[38:41]
	v_mfma_f32_16x16x32_bf16 v[26:29], v[150:153], v[182:185], v[26:29]
	v_mfma_f32_16x16x32_bf16 v[22:25], v[158:161], v[182:185], v[22:25]
	v_mfma_f32_16x16x32_bf16 v[10:13], v[150:153], v[190:193], v[10:13]
	v_mfma_f32_16x16x32_bf16 v[6:9], v[158:161], v[190:193], v[6:9]
	v_mfma_f32_16x16x32_bf16 v[58:61], v[154:157], v[170:173], v[58:61]
	v_mfma_f32_16x16x32_bf16 v[54:57], v[162:165], v[170:173], v[54:57]
	v_mfma_f32_16x16x32_bf16 v[42:45], v[154:157], v[178:181], v[42:45]
	v_mfma_f32_16x16x32_bf16 v[38:41], v[162:165], v[178:181], v[38:41]
	v_mfma_f32_16x16x32_bf16 v[26:29], v[154:157], v[186:189], v[26:29]
	v_mfma_f32_16x16x32_bf16 v[22:25], v[162:165], v[186:189], v[22:25]
	v_mfma_f32_16x16x32_bf16 v[10:13], v[154:157], v[194:197], v[10:13]
	v_mfma_f32_16x16x32_bf16 v[6:9], v[162:165], v[194:197], v[6:9]
	s_setprio 0
	s_barrier
	s_add_i32 s60, s60, 2
	s_add_u32 s38, s38, 0x100
	s_addc_u32 s39, s39, 0
	s_add_u32 s58, s58, 0x100
	s_addc_u32 s59, s59, 0
	s_cmp_gt_u32 s60, 29
	s_cbranch_scc0 .LBB0_513
	s_and_b64 vcc, exec, s[16:17]
	s_cbranch_vccz .LBB0_516
	s_barrier

; #define PG8_STAGE(bufoff, gbase, voff) do { _Pragma("unroll") for (int _i = 0; _i < 2; ++_i) \
;         __builtin_amdgcn_global_load_lds((const unsigned*)((const char*)(gbase) + (voff)[_i]), (LAS unsigned*)(lds + (bufoff) + ldsw + _i * 8192), 16, 0, 0); } while (0)
; #define PG8_LDA(dst, b, h) do { _Pragma("unroll") for (int m = 0; m < 4; ++m) _Pragma("unroll") for (int k = 0; k < 2; ++k) dst[m][k] = *(const LAS bf16x8*)(lds + PG8_SA(b, h) + aoff + m * 2048 + k * 1024); } while (0)
; #define PG8_LDB(dst, b, h) do { _Pragma("unroll") for (int n = 0; n < 2; ++n) _Pragma("unroll") for (int k = 0; k < 2; ++k) dst[n][k] = *(const LAS bf16x8*)(lds + PG8_SB(b, h) + boff + n * 2048 + k * 1024); } while (0)
; #define PG8_MMA(ai, bj, At, Bt) do { __builtin_amdgcn_s_setprio(1); _Pragma("unroll") for (int m = 0; m < 4; ++m) _Pragma("unroll") for (int n = 0; n < 2; ++n) _Pragma("unroll") for (int k = 0; k < 2; ++k) \
;         acc[ai][bj][m][n] = __builtin_amdgcn_mfma_f32_16x16x32_bf16(Bt[n][k], At[m][k], acc[ai][bj][m][n], 0, 0, 0); __builtin_amdgcn_s_setprio(0); } while (0)
; #define PG8_WAIT_V(n) asm volatile("s_waitcnt vmcnt(" #n ")" ::: "memory")
; #define PG8_WAIT_L(n) asm volatile("s_waitcnt lgkmcnt(" #n ")" ::: "memory")
; #define PG8_BAR __builtin_amdgcn_s_barrier()
; template <class Epi, class Sched>
; __device__ __forceinline__ void gemm_phase(LAS unsigned char* lds, const Gemm g, const Sched& S, const Epi& E) {
;     ...
;         for (int t = 0; t < nt; t += 2) {
;             const bool last = (t == nt - 2);
;             const char* a1 = cA + (size_t)(t + 1) * kstep;
;             const char* a2 = last ? nA : cA + (size_t)(t + 2) * kstep; const char* b2 = last ? nB : cB + (size_t)(t + 2) * kstep;
;             const char* a3 = a2 + kstep; const char* b3 = b2 + kstep;
;             if (last && has_next) S.a_ready(nxt);
;             PG8_LDB(B0, 0, 0); PG8_LDB(B1, 0, 1); PG8_SCHED; PG8_LDA(At, 0, 0); PG8_STAGE(PG8_SA(1, 1), a1 + hstepA, voffA);
;             PG8_WAIT_V(8); PG8_WAIT_L(0); PG8_BAR; PG8_MMA(0, 0, At, B0); PG8_MMA(0, 1, At, B1); PG8_BAR; PG8_SCHED;
;             PG8_LDA(At, 0, 1); PG8_STAGE(PG8_SB(0, 0), b2, voffB); PG8_STAGE(PG8_SB(0, 1), b2 + hstepB, voffB); PG8_STAGE(PG8_SA(0, 0), a2, voffA);
;             PG8_WAIT_V(8); PG8_WAIT_L(0); PG8_BAR; PG8_MMA(1, 0, At, B0); PG8_MMA(1, 1, At, B1); PG8_BAR; PG8_SCHED;
.LBB0_655:
	s_add_u32 s28, s26, 0xfff80080
	s_addc_u32 s29, s27, -1
	s_add_i32 s57, 0, 0x10000
	s_cmp_eq_u32 s56, 28
	s_cselect_b32 s41, s17, s29
	s_cselect_b32 s40, s23, s28
	v_add_u32_e32 v4, s57, v231
	s_cselect_b32 s29, s15, s55
	s_cselect_b32 s28, s25, s34
	s_add_i32 s60, 0, 0x14000
	ds_read_b128 v[134:137], v4
	ds_read_b128 v[138:141], v4 offset:1024
	ds_read_b128 v[142:145], v4 offset:2048
	ds_read_b128 v[146:149], v4 offset:3072
	v_add_u32_e32 v4, s60, v231
	ds_read_b128 v[150:153], v4
	ds_read_b128 v[154:157], v4 offset:1024
	ds_read_b128 v[158:161], v4 offset:2048
	ds_read_b128 v[162:165], v4 offset:3072
	v_lshl_add_u64 v[236:237], s[26:27], 0, v[196:197]
	s_add_i32 m0, s47, 0xc000
	ds_read_b128 v[166:169], v235
	ds_read_b128 v[170:173], v235 offset:1024
	ds_read_b128 v[174:177], v235 offset:2048
	ds_read_b128 v[178:181], v235 offset:3072
	ds_read_b128 v[214:217], v235 offset:4096
	ds_read_b128 v[218:221], v235 offset:5120
	ds_read_b128 v[222:225], v235 offset:6144
	ds_read_b128 v[226:229], v235 offset:7168
	global_load_lds_dwordx4 v[236:237], off
	v_lshl_add_u64 v[236:237], s[26:27], 0, v[212:213]
	s_add_i32 m0, s47, 0xe000
	s_nop 0
	global_load_lds_dwordx4 v[236:237], off
	s_waitcnt vmcnt(8)
	s_waitcnt lgkmcnt(0)
	s_barrier
	s_setprio 1
	v_mfma_f32_16x16x32_bf16 v[130:133], v[134:137], v[166:169], v[130:133]
	v_mfma_f32_16x16x32_bf16 v[126:129], v[142:145], v[166:169], v[126:129]
	v_mfma_f32_16x16x32_bf16 v[114:117], v[134:137], v[174:177], v[114:117]
	v_mfma_f32_16x16x32_bf16 v[110:113], v[142:145], v[174:177], v[110:113]
	v_mfma_f32_16x16x32_bf16 v[98:101], v[134:137], v[214:217], v[98:101]
	v_mfma_f32_16x16x32_bf16 v[94:97], v[142:145], v[214:217], v[94:97]
	v_mfma_f32_16x16x32_bf16 v[82:85], v[134:137], v[222:225], v[82:85]
	v_mfma_f32_16x16x32_bf16 v[78:81], v[142:145], v[222:225], v[78:81]
	v_mfma_f32_16x16x32_bf16 v[130:133], v[138:141], v[170:173], v[130:133]
	v_mfma_f32_16x16x32_bf16 v[126:129], v[146:149], v[170:173], v[126:129]
	v_mfma_f32_16x16x32_bf16 v[114:117], v[138:141], v[178:181], v[114:117]
	v_mfma_f32_16x16x32_bf16 v[110:113], v[146:149], v[178:181], v[110:113]
	v_mfma_f32_16x16x32_bf16 v[98:101], v[138:141], v[218:221], v[98:101]
	v_mfma_f32_16x16x32_bf16 v[94:97], v[146:149], v[218:221], v[94:97]
	v_mfma_f32_16x16x32_bf16 v[82:85], v[138:141], v[226:229], v[82:85]
	v_mfma_f32_16x16x32_bf16 v[78:81], v[146:149], v[226:229], v[78:81]
	v_mfma_f32_16x16x32_bf16 v[122:125], v[150:153], v[166:169], v[122:125]
	v_mfma_f32_16x16x32_bf16 v[118:121], v[158:161], v[166:169], v[118:121]
	v_mfma_f32_16x16x32_bf16 v[106:109], v[150:153], v[174:177], v[106:109]
	v_mfma_f32_16x16x32_bf16 v[102:105], v[158:161], v[174:177], v[102:105]
	v_mfma_f32_16x16x32_bf16 v[90:93], v[150:153], v[214:217], v[90:93]
	v_mfma_f32_16x16x32_bf16 v[86:89], v[158:161], v[214:217], v[86:89]
	v_mfma_f32_16x16x32_bf16 v[74:77], v[150:153], v[222:225], v[74:77]
	v_mfma_f32_16x16x32_bf16 v[70:73], v[158:161], v[222:225], v[70:73]
	v_mfma_f32_16x16x32_bf16 v[122:125], v[154:157], v[170:173], v[122:125]
	v_mfma_f32_16x16x32_bf16 v[118:121], v[162:165], v[170:173], v[118:121]
	v_mfma_f32_16x16x32_bf16 v[106:109], v[154:157], v[178:181], v[106:109]
	v_mfma_f32_16x16x32_bf16 v[102:105], v[162:165], v[178:181], v[102:105]
	v_mfma_f32_16x16x32_bf16 v[90:93], v[154:157], v[218:221], v[90:93]
	v_mfma_f32_16x16x32_bf16 v[86:89], v[162:165], v[218:221], v[86:89]
	v_mfma_f32_16x16x32_bf16 v[74:77], v[154:157], v[226:229], v[74:77]
	v_mfma_f32_16x16x32_bf16 v[70:73], v[162:165], v[226:229], v[70:73]
	s_setprio 0
	s_barrier
	s_add_i32 s57, s57, s46
	v_lshl_add_u64 v[236:237], s[28:29], 0, v[182:183]
	s_mov_b32 m0, s57
	ds_read_b128 v[166:169], v235 offset:16384
	ds_read_b128 v[170:173], v235 offset:17408
	ds_read_b128 v[174:177], v235 offset:18432
	ds_read_b128 v[178:181], v235 offset:19456
	ds_read_b128 v[214:217], v235 offset:20480
	ds_read_b128 v[218:221], v235 offset:21504
	ds_read_b128 v[222:225], v235 offset:22528
	ds_read_b128 v[226:229], v235 offset:23552
	global_load_lds_dwordx4 v[236:237], off
	s_add_i32 m0, s57, 0x2000
	s_add_u32 s58, s28, 0x80000
	v_lshl_add_u64 v[238:239], s[28:29], 0, v[186:187]
	s_addc_u32 s59, s29, 0
	s_add_i32 s57, s60, s46
	global_load_lds_dwordx4 v[238:239], off
	v_lshl_add_u64 v[240:241], s[58:59], 0, v[182:183]
	s_mov_b32 m0, s57
	v_lshl_add_u64 v[242:243], s[40:41], 0, v[184:185]
	global_load_lds_dwordx4 v[240:241], off
	v_lshl_add_u64 v[240:241], s[58:59], 0, v[186:187]
	s_add_i32 m0, s57, 0x2000
	s_nop 0
	global_load_lds_dwordx4 v[240:241], off
	v_lshl_add_u64 v[240:241], s[40:41], 0, v[2:3]
	s_mov_b32 m0, s47
	s_nop 0
	global_load_lds_dwordx4 v[240:241], off
	s_mov_b32 m0, s48
	s_nop 0
	global_load_lds_dwordx4 v[242:243], off
	s_waitcnt vmcnt(8)
	s_waitcnt lgkmcnt(0)
	s_barrier
; #define PG8_STAGE(bufoff, gbase, voff) do { _Pragma("unroll") for (int _i = 0; _i < 2; ++_i) \
;         __builtin_amdgcn_global_load_lds((const unsigned*)((const char*)(gbase) + (voff)[_i]), (LAS unsigned*)(lds + (bufoff) + ldsw + _i * 8192), 16, 0, 0); } while (0)
; #define PG8_LDA(dst, b, h) do { _Pragma("unroll") for (int m = 0; m < 4; ++m) _Pragma("unroll") for (int k = 0; k < 2; ++k) dst[m][k] = *(const LAS bf16x8*)(lds + PG8_SA(b, h) + aoff + m * 2048 + k * 1024); } while (0)
; #define PG8_LDB(dst, b, h) do { _Pragma("unroll") for (int n = 0; n < 2; ++n) _Pragma("unroll") for (int k = 0; k < 2; ++k) dst[n][k] = *(const LAS bf16x8*)(lds + PG8_SB(b, h) + boff + n * 2048 + k * 1024); } while (0)
; #define PG8_MMA(ai, bj, At, Bt) do { __builtin_amdgcn_s_setprio(1); _Pragma("unroll") for (int m = 0; m < 4; ++m) _Pragma("unroll") for (int n = 0; n < 2; ++n) _Pragma("unroll") for (int k = 0; k < 2; ++k) \
;         acc[ai][bj][m][n] = __builtin_amdgcn_mfma_f32_16x16x32_bf16(Bt[n][k], At[m][k], acc[ai][bj][m][n], 0, 0, 0); __builtin_amdgcn_s_setprio(0); } while (0)
; #define PG8_WAIT_V(n) asm volatile("s_waitcnt vmcnt(" #n ")" ::: "memory")
; #define PG8_WAIT_L(n) asm volatile("s_waitcnt lgkmcnt(" #n ")" ::: "memory")
; #define PG8_BAR __builtin_amdgcn_s_barrier()
; #define PG8_SCHED __builtin_amdgcn_sched_barrier(0)
; template <class Epi, class Sched>
; __device__ __forceinline__ void gemm_phase(LAS unsigned char* lds, const Gemm g, const Sched& S, const Epi& E) {
;     ...
;             PG8_WAIT_V(8); PG8_WAIT_L(0); PG8_BAR; PG8_MMA(1, 0, At, B0); PG8_MMA(1, 1, At, B1); PG8_BAR; PG8_SCHED;
;             PG8_LDB(B0, 1, 0); PG8_LDB(B1, 1, 1); PG8_SCHED; PG8_LDA(At, 1, 0); PG8_STAGE(PG8_SA(0, 1), a2 + hstepA, voffA);
;             PG8_WAIT_V(8); PG8_WAIT_L(0); PG8_BAR; PG8_MMA(0, 0, At, B0); PG8_MMA(0, 1, At, B1); PG8_BAR; PG8_SCHED;
	s_setprio 1
	v_mfma_f32_16x16x32_bf16 v[66:69], v[134:137], v[166:169], v[66:69]
	v_mfma_f32_16x16x32_bf16 v[62:65], v[142:145], v[166:169], v[62:65]
	v_mfma_f32_16x16x32_bf16 v[50:53], v[134:137], v[174:177], v[50:53]
	v_mfma_f32_16x16x32_bf16 v[46:49], v[142:145], v[174:177], v[46:49]
	v_mfma_f32_16x16x32_bf16 v[34:37], v[134:137], v[214:217], v[34:37]
	v_mfma_f32_16x16x32_bf16 v[30:33], v[142:145], v[214:217], v[30:33]
	v_mfma_f32_16x16x32_bf16 v[18:21], v[134:137], v[222:225], v[18:21]
	v_mfma_f32_16x16x32_bf16 v[14:17], v[142:145], v[222:225], v[14:17]
	v_mfma_f32_16x16x32_bf16 v[66:69], v[138:141], v[170:173], v[66:69]
	v_mfma_f32_16x16x32_bf16 v[62:65], v[146:149], v[170:173], v[62:65]
	v_mfma_f32_16x16x32_bf16 v[50:53], v[138:141], v[178:181], v[50:53]
	v_mfma_f32_16x16x32_bf16 v[46:49], v[146:149], v[178:181], v[46:49]
	v_mfma_f32_16x16x32_bf16 v[34:37], v[138:141], v[218:221], v[34:37]
	v_mfma_f32_16x16x32_bf16 v[30:33], v[146:149], v[218:221], v[30:33]
	v_mfma_f32_16x16x32_bf16 v[18:21], v[138:141], v[226:229], v[18:21]
	v_mfma_f32_16x16x32_bf16 v[14:17], v[146:149], v[226:229], v[14:17]
	v_mfma_f32_16x16x32_bf16 v[58:61], v[150:153], v[166:169], v[58:61]
	v_mfma_f32_16x16x32_bf16 v[54:57], v[158:161], v[166:169], v[54:57]
	v_mfma_f32_16x16x32_bf16 v[42:45], v[150:153], v[174:177], v[42:45]
	v_mfma_f32_16x16x32_bf16 v[38:41], v[158:161], v[174:177], v[38:41]
	v_mfma_f32_16x16x32_bf16 v[26:29], v[150:153], v[214:217], v[26:29]
	v_mfma_f32_16x16x32_bf16 v[22:25], v[158:161], v[214:217], v[22:25]
	v_mfma_f32_16x16x32_bf16 v[10:13], v[150:153], v[222:225], v[10:13]
	v_mfma_f32_16x16x32_bf16 v[6:9], v[158:161], v[222:225], v[6:9]
	v_mfma_f32_16x16x32_bf16 v[58:61], v[154:157], v[170:173], v[58:61]
	v_mfma_f32_16x16x32_bf16 v[54:57], v[162:165], v[170:173], v[54:57]
	v_mfma_f32_16x16x32_bf16 v[42:45], v[154:157], v[178:181], v[42:45]
	v_mfma_f32_16x16x32_bf16 v[38:41], v[162:165], v[178:181], v[38:41]
	v_mfma_f32_16x16x32_bf16 v[26:29], v[154:157], v[218:221], v[26:29]
	v_mfma_f32_16x16x32_bf16 v[22:25], v[162:165], v[218:221], v[22:25]
	v_mfma_f32_16x16x32_bf16 v[10:13], v[154:157], v[226:229], v[10:13]
	v_mfma_f32_16x16x32_bf16 v[6:9], v[162:165], v[226:229], v[6:9]
	s_setprio 0
	s_barrier
	s_add_i32 s57, 0, 0x18000
	v_add_u32_e32 v4, s57, v231
	s_add_i32 s58, 0, 0x1c000
	ds_read_b128 v[134:137], v4
	ds_read_b128 v[138:141], v4 offset:1024
	ds_read_b128 v[142:145], v4 offset:2048
	ds_read_b128 v[146:149], v4 offset:3072
	v_add_u32_e32 v4, s58, v231
	ds_read_b128 v[150:153], v4
	ds_read_b128 v[154:157], v4 offset:1024
	ds_read_b128 v[158:161], v4 offset:2048
	ds_read_b128 v[162:165], v4 offset:3072
	s_add_u32 s40, s40, 0x80000
	s_addc_u32 s41, s41, 0
	s_mov_b32 m0, s49
	v_lshl_add_u64 v[244:245], s[40:41], 0, v[2:3]
	ds_read_b128 v[166:169], v235 offset:32768
	ds_read_b128 v[170:173], v235 offset:33792
	ds_read_b128 v[174:177], v235 offset:34816
	ds_read_b128 v[178:181], v235 offset:35840
	ds_read_b128 v[214:217], v235 offset:36864
	ds_read_b128 v[218:221], v235 offset:37888
	ds_read_b128 v[222:225], v235 offset:38912
	ds_read_b128 v[226:229], v235 offset:39936
	global_load_lds_dwordx4 v[244:245], off
	v_lshl_add_u64 v[244:245], s[40:41], 0, v[184:185]
	s_mov_b32 m0, s50
	s_nop 0
	global_load_lds_dwordx4 v[244:245], off
	s_waitcnt vmcnt(8)
	s_waitcnt lgkmcnt(0)
	s_barrier
	s_setprio 1
	v_mfma_f32_16x16x32_bf16 v[130:133], v[134:137], v[166:169], v[130:133]
	v_mfma_f32_16x16x32_bf16 v[126:129], v[142:145], v[166:169], v[126:129]
	v_mfma_f32_16x16x32_bf16 v[114:117], v[134:137], v[174:177], v[114:117]
	v_mfma_f32_16x16x32_bf16 v[110:113], v[142:145], v[174:177], v[110:113]
	v_mfma_f32_16x16x32_bf16 v[98:101], v[134:137], v[214:217], v[98:101]
	v_mfma_f32_16x16x32_bf16 v[94:97], v[142:145], v[214:217], v[94:97]
	v_mfma_f32_16x16x32_bf16 v[82:85], v[134:137], v[222:225], v[82:85]
	v_mfma_f32_16x16x32_bf16 v[78:81], v[142:145], v[222:225], v[78:81]
	v_mfma_f32_16x16x32_bf16 v[130:133], v[138:141], v[170:173], v[130:133]
	v_mfma_f32_16x16x32_bf16 v[126:129], v[146:149], v[170:173], v[126:129]
	v_mfma_f32_16x16x32_bf16 v[114:117], v[138:141], v[178:181], v[114:117]
	v_mfma_f32_16x16x32_bf16 v[110:113], v[146:149], v[178:181], v[110:113]
	v_mfma_f32_16x16x32_bf16 v[98:101], v[138:141], v[218:221], v[98:101]
	v_mfma_f32_16x16x32_bf16 v[94:97], v[146:149], v[218:221], v[94:97]
	v_mfma_f32_16x16x32_bf16 v[82:85], v[138:141], v[226:229], v[82:85]
	v_mfma_f32_16x16x32_bf16 v[78:81], v[146:149], v[226:229], v[78:81]
	v_mfma_f32_16x16x32_bf16 v[122:125], v[150:153], v[166:169], v[122:125]
	v_mfma_f32_16x16x32_bf16 v[118:121], v[158:161], v[166:169], v[118:121]
	v_mfma_f32_16x16x32_bf16 v[106:109], v[150:153], v[174:177], v[106:109]
	v_mfma_f32_16x16x32_bf16 v[102:105], v[158:161], v[174:177], v[102:105]
	v_mfma_f32_16x16x32_bf16 v[90:93], v[150:153], v[214:217], v[90:93]
	v_mfma_f32_16x16x32_bf16 v[86:89], v[158:161], v[214:217], v[86:89]
	v_mfma_f32_16x16x32_bf16 v[74:77], v[150:153], v[222:225], v[74:77]
	v_mfma_f32_16x16x32_bf16 v[70:73], v[158:161], v[222:225], v[70:73]
	v_mfma_f32_16x16x32_bf16 v[122:125], v[154:157], v[170:173], v[122:125]
	v_mfma_f32_16x16x32_bf16 v[118:121], v[162:165], v[170:173], v[118:121]
	v_mfma_f32_16x16x32_bf16 v[106:109], v[154:157], v[178:181], v[106:109]
	v_mfma_f32_16x16x32_bf16 v[102:105], v[162:165], v[178:181], v[102:105]
	v_mfma_f32_16x16x32_bf16 v[90:93], v[154:157], v[218:221], v[90:93]
	v_mfma_f32_16x16x32_bf16 v[86:89], v[162:165], v[218:221], v[86:89]
	v_mfma_f32_16x16x32_bf16 v[74:77], v[154:157], v[226:229], v[74:77]
	v_mfma_f32_16x16x32_bf16 v[70:73], v[162:165], v[226:229], v[70:73]
	s_setprio 0
	s_barrier
; #define PG8_STAGE(bufoff, gbase, voff) do { _Pragma("unroll") for (int _i = 0; _i < 2; ++_i) \
;         __builtin_amdgcn_global_load_lds((const unsigned*)((const char*)(gbase) + (voff)[_i]), (LAS unsigned*)(lds + (bufoff) + ldsw + _i * 8192), 16, 0, 0); } while (0)
; #define PG8_LDA(dst, b, h) do { _Pragma("unroll") for (int m = 0; m < 4; ++m) _Pragma("unroll") for (int k = 0; k < 2; ++k) dst[m][k] = *(const LAS bf16x8*)(lds + PG8_SA(b, h) + aoff + m * 2048 + k * 1024); } while (0)
; #define PG8_MMA(ai, bj, At, Bt) do { __builtin_amdgcn_s_setprio(1); _Pragma("unroll") for (int m = 0; m < 4; ++m) _Pragma("unroll") for (int n = 0; n < 2; ++n) _Pragma("unroll") for (int k = 0; k < 2; ++k) \
;         acc[ai][bj][m][n] = __builtin_amdgcn_mfma_f32_16x16x32_bf16(Bt[n][k], At[m][k], acc[ai][bj][m][n], 0, 0, 0); __builtin_amdgcn_s_setprio(0); } while (0)
; #define PG8_WAIT_V(n) asm volatile("s_waitcnt vmcnt(" #n ")" ::: "memory")
; #define PG8_WAIT_L(n) asm volatile("s_waitcnt lgkmcnt(" #n ")" ::: "memory")
; #define PG8_BAR __builtin_amdgcn_s_barrier()
; #define PG8_SCHED __builtin_amdgcn_sched_barrier(0)
; template <class Epi, class Sched>
; __device__ __forceinline__ void gemm_phase(LAS unsigned char* lds, const Gemm g, const Sched& S, const Epi& E) {
;     ...
;             PG8_LDA(At, 1, 1); PG8_STAGE(PG8_SB(1, 0), b3, voffB); PG8_STAGE(PG8_SB(1, 1), b3 + hstepB, voffB); PG8_STAGE(PG8_SA(1, 0), a3, voffA);
;             PG8_WAIT_V(8); PG8_WAIT_L(0); PG8_BAR; PG8_MMA(1, 0, At, B0); PG8_MMA(1, 1, At, B1); PG8_BAR; PG8_SCHED;
;         }
;         if (wr == 0) PG8_BAR;
	s_add_i32 s40, s57, s46
	v_lshl_add_u64 v[236:237], v[236:237], 0, s[36:37]
	s_mov_b32 m0, s40
	ds_read_b128 v[166:169], v235 offset:49152
	ds_read_b128 v[170:173], v235 offset:50176
	ds_read_b128 v[174:177], v235 offset:51200
	ds_read_b128 v[178:181], v235 offset:52224
	ds_read_b128 v[214:217], v235 offset:53248
	ds_read_b128 v[218:221], v235 offset:54272
	ds_read_b128 v[222:225], v235 offset:55296
	ds_read_b128 v[226:229], v235 offset:56320
	global_load_lds_dwordx4 v[236:237], off
	s_add_i32 m0, s40, 0x2000
	s_add_u32 s28, s28, 0x80080
	v_lshl_add_u64 v[236:237], v[238:239], 0, s[36:37]
	s_addc_u32 s29, s29, 0
	s_add_i32 s40, s58, s46
	global_load_lds_dwordx4 v[236:237], off
	v_lshl_add_u64 v[236:237], s[28:29], 0, v[182:183]
	s_mov_b32 m0, s40
	s_nop 0
	global_load_lds_dwordx4 v[236:237], off
	v_lshl_add_u64 v[236:237], s[28:29], 0, v[186:187]
	s_add_i32 m0, s40, 0x2000
	s_nop 0
	global_load_lds_dwordx4 v[236:237], off
	v_lshl_add_u64 v[236:237], v[240:241], 0, s[36:37]
	s_mov_b32 m0, s52
	s_nop 0
	global_load_lds_dwordx4 v[236:237], off
	v_lshl_add_u64 v[236:237], v[242:243], 0, s[36:37]
	s_mov_b32 m0, s53
	s_nop 0
	global_load_lds_dwordx4 v[236:237], off
	s_waitcnt vmcnt(8)
	s_waitcnt lgkmcnt(0)
	s_barrier
	s_setprio 1
	v_mfma_f32_16x16x32_bf16 v[66:69], v[134:137], v[166:169], v[66:69]
	v_mfma_f32_16x16x32_bf16 v[62:65], v[142:145], v[166:169], v[62:65]
	v_mfma_f32_16x16x32_bf16 v[50:53], v[134:137], v[174:177], v[50:53]
	v_mfma_f32_16x16x32_bf16 v[46:49], v[142:145], v[174:177], v[46:49]
	v_mfma_f32_16x16x32_bf16 v[34:37], v[134:137], v[214:217], v[34:37]
	v_mfma_f32_16x16x32_bf16 v[30:33], v[142:145], v[214:217], v[30:33]
	v_mfma_f32_16x16x32_bf16 v[18:21], v[134:137], v[222:225], v[18:21]
	v_mfma_f32_16x16x32_bf16 v[14:17], v[142:145], v[222:225], v[14:17]
	v_mfma_f32_16x16x32_bf16 v[66:69], v[138:141], v[170:173], v[66:69]
	v_mfma_f32_16x16x32_bf16 v[62:65], v[146:149], v[170:173], v[62:65]
	v_mfma_f32_16x16x32_bf16 v[50:53], v[138:141], v[178:181], v[50:53]
	v_mfma_f32_16x16x32_bf16 v[46:49], v[146:149], v[178:181], v[46:49]
	v_mfma_f32_16x16x32_bf16 v[34:37], v[138:141], v[218:221], v[34:37]
	v_mfma_f32_16x16x32_bf16 v[30:33], v[146:149], v[218:221], v[30:33]
	v_mfma_f32_16x16x32_bf16 v[18:21], v[138:141], v[226:229], v[18:21]
	v_mfma_f32_16x16x32_bf16 v[14:17], v[146:149], v[226:229], v[14:17]
	v_mfma_f32_16x16x32_bf16 v[58:61], v[150:153], v[166:169], v[58:61]
	v_mfma_f32_16x16x32_bf16 v[54:57], v[158:161], v[166:169], v[54:57]
	v_mfma_f32_16x16x32_bf16 v[42:45], v[150:153], v[174:177], v[42:45]
	v_mfma_f32_16x16x32_bf16 v[38:41], v[158:161], v[174:177], v[38:41]
	v_mfma_f32_16x16x32_bf16 v[26:29], v[150:153], v[214:217], v[26:29]
	v_mfma_f32_16x16x32_bf16 v[22:25], v[158:161], v[214:217], v[22:25]
	v_mfma_f32_16x16x32_bf16 v[10:13], v[150:153], v[222:225], v[10:13]
	v_mfma_f32_16x16x32_bf16 v[6:9], v[158:161], v[222:225], v[6:9]
	v_mfma_f32_16x16x32_bf16 v[58:61], v[154:157], v[170:173], v[58:61]
	v_mfma_f32_16x16x32_bf16 v[54:57], v[162:165], v[170:173], v[54:57]
	v_mfma_f32_16x16x32_bf16 v[42:45], v[154:157], v[178:181], v[42:45]
	v_mfma_f32_16x16x32_bf16 v[38:41], v[162:165], v[178:181], v[38:41]
	v_mfma_f32_16x16x32_bf16 v[26:29], v[154:157], v[218:221], v[26:29]
	v_mfma_f32_16x16x32_bf16 v[22:25], v[162:165], v[218:221], v[22:25]
	v_mfma_f32_16x16x32_bf16 v[10:13], v[154:157], v[226:229], v[10:13]
	v_mfma_f32_16x16x32_bf16 v[6:9], v[162:165], v[226:229], v[6:9]
	s_setprio 0
	s_barrier
	s_add_i32 s56, s56, 2
	s_add_u32 s26, s26, 0x100
	s_addc_u32 s27, s27, 0
	s_add_u32 s34, s34, 0x100
	s_addc_u32 s55, s55, 0
	s_cmp_gt_u32 s56, 29
	s_cbranch_scc0 .LBB0_655
	s_and_b64 vcc, exec, s[12:13]
	s_cbranch_vccz .LBB0_658
	s_barrier

; #define PG8_STAGE(bufoff, gbase, voff) do { _Pragma("unroll") for (int _i = 0; _i < 2; ++_i) \
;         __builtin_amdgcn_global_load_lds((const unsigned*)((const char*)(gbase) + (voff)[_i]), (LAS unsigned*)(lds + (bufoff) + ldsw + _i * 8192), 16, 0, 0); } while (0)
; #define PG8_LDA(dst, b, h) do { _Pragma("unroll") for (int m = 0; m < 4; ++m) _Pragma("unroll") for (int k = 0; k < 2; ++k) dst[m][k] = *(const LAS bf16x8*)(lds + PG8_SA(b, h) + aoff + m * 2048 + k * 1024); } while (0)
; #define PG8_LDB(dst, b, h) do { _Pragma("unroll") for (int n = 0; n < 2; ++n) _Pragma("unroll") for (int k = 0; k < 2; ++k) dst[n][k] = *(const LAS bf16x8*)(lds + PG8_SB(b, h) + boff + n * 2048 + k * 1024); } while (0)
; #define PG8_MMA(ai, bj, At, Bt) do { __builtin_amdgcn_s_setprio(1); _Pragma("unroll") for (int m = 0; m < 4; ++m) _Pragma("unroll") for (int n = 0; n < 2; ++n) _Pragma("unroll") for (int k = 0; k < 2; ++k) \
;         acc[ai][bj][m][n] = __builtin_amdgcn_mfma_f32_16x16x32_bf16(Bt[n][k], At[m][k], acc[ai][bj][m][n], 0, 0, 0); __builtin_amdgcn_s_setprio(0); } while (0)
; #define PG8_WAIT_V(n) asm volatile("s_waitcnt vmcnt(" #n ")" ::: "memory")
; #define PG8_WAIT_L(n) asm volatile("s_waitcnt lgkmcnt(" #n ")" ::: "memory")
; #define PG8_BAR __builtin_amdgcn_s_barrier()
; template <class Epi, class Sched>
; __device__ __forceinline__ void gemm_phase(LAS unsigned char* lds, const Gemm g, const Sched& S, const Epi& E) {
;     ...
;         for (int t = 0; t < nt; t += 2) {
;             const bool last = (t == nt - 2);
;             const char* a1 = cA + (size_t)(t + 1) * kstep;
;             const char* a2 = last ? nA : cA + (size_t)(t + 2) * kstep; const char* b2 = last ? nB : cB + (size_t)(t + 2) * kstep;
;             const char* a3 = a2 + kstep; const char* b3 = b2 + kstep;
;             if (last && has_next) S.a_ready(nxt);
;             PG8_LDB(B0, 0, 0); PG8_LDB(B1, 0, 1); PG8_SCHED; PG8_LDA(At, 0, 0); PG8_STAGE(PG8_SA(1, 1), a1 + hstepA, voffA);
;             PG8_WAIT_V(8); PG8_WAIT_L(0); PG8_BAR; PG8_MMA(0, 0, At, B0); PG8_MMA(0, 1, At, B1); PG8_BAR; PG8_SCHED;
;             PG8_LDA(At, 0, 1); PG8_STAGE(PG8_SB(0, 0), b2, voffB); PG8_STAGE(PG8_SB(0, 1), b2 + hstepB, voffB); PG8_STAGE(PG8_SA(0, 0), a2, voffA);
;             PG8_WAIT_V(8); PG8_WAIT_L(0); PG8_BAR; PG8_MMA(1, 0, At, B0); PG8_MMA(1, 1, At, B1); PG8_BAR; PG8_SCHED;
.LBB0_1009:
	s_add_i32 s43, s48, 2
	s_add_u32 s70, s26, s46
	s_addc_u32 s49, s27, s47
	s_add_u32 s72, s24, s46
	s_addc_u32 s71, s25, s47
	s_add_i32 s73, 0, 0x10000
	s_cmp_eq_u32 s65, s48
	s_cselect_b32 s49, s5, s49
	s_cselect_b32 s48, s4, s70
	v_add_u32_e32 v4, s73, v148
	s_cselect_b32 s71, s45, s71
	s_cselect_b32 s70, s44, s72
	s_add_i32 s72, 0, 0x14000
	ds_read_b128 v[150:153], v4
	ds_read_b128 v[154:157], v4 offset:1024
	ds_read_b128 v[158:161], v4 offset:2048
	ds_read_b128 v[162:165], v4 offset:3072
	v_add_u32_e32 v4, s72, v148
	ds_read_b128 v[170:173], v4
	ds_read_b128 v[174:177], v4 offset:1024
	ds_read_b128 v[178:181], v4 offset:2048
	ds_read_b128 v[182:185], v4 offset:3072
	v_lshl_add_u64 v[166:167], s[26:27], 0, v[146:147]
	s_add_i32 m0, s58, 0xc000
	ds_read_b128 v[186:189], v149
	ds_read_b128 v[190:193], v149 offset:1024
	ds_read_b128 v[194:197], v149 offset:2048
	ds_read_b128 v[212:215], v149 offset:3072
	ds_read_b128 v[216:219], v149 offset:4096
	ds_read_b128 v[220:223], v149 offset:5120
	ds_read_b128 v[224:227], v149 offset:6144
	ds_read_b128 v[228:231], v149 offset:7168
	global_load_lds_dwordx4 v[166:167], off
	v_lshl_add_u64 v[166:167], s[26:27], 0, v[2:3]
	s_add_i32 m0, s58, 0xe000
	s_nop 0
	global_load_lds_dwordx4 v[166:167], off
	s_waitcnt vmcnt(8)
	s_waitcnt lgkmcnt(0)
	s_barrier
	s_setprio 1
	v_mfma_f32_16x16x32_bf16 v[130:133], v[150:153], v[186:189], v[130:133]
	v_mfma_f32_16x16x32_bf16 v[126:129], v[158:161], v[186:189], v[126:129]
	v_mfma_f32_16x16x32_bf16 v[122:125], v[150:153], v[194:197], v[122:125]
	v_mfma_f32_16x16x32_bf16 v[118:121], v[158:161], v[194:197], v[118:121]
	v_mfma_f32_16x16x32_bf16 v[110:113], v[150:153], v[216:219], v[110:113]
	v_mfma_f32_16x16x32_bf16 v[106:109], v[158:161], v[216:219], v[106:109]
	v_mfma_f32_16x16x32_bf16 v[98:101], v[150:153], v[224:227], v[98:101]
	v_mfma_f32_16x16x32_bf16 v[90:93], v[158:161], v[224:227], v[90:93]
	v_mfma_f32_16x16x32_bf16 v[130:133], v[154:157], v[190:193], v[130:133]
	v_mfma_f32_16x16x32_bf16 v[126:129], v[162:165], v[190:193], v[126:129]
	v_mfma_f32_16x16x32_bf16 v[122:125], v[154:157], v[212:215], v[122:125]
	v_mfma_f32_16x16x32_bf16 v[118:121], v[162:165], v[212:215], v[118:121]
	v_mfma_f32_16x16x32_bf16 v[110:113], v[154:157], v[220:223], v[110:113]
	v_mfma_f32_16x16x32_bf16 v[106:109], v[162:165], v[220:223], v[106:109]
	v_mfma_f32_16x16x32_bf16 v[98:101], v[154:157], v[228:231], v[98:101]
	v_mfma_f32_16x16x32_bf16 v[90:93], v[162:165], v[228:231], v[90:93]
	v_mfma_f32_16x16x32_bf16 v[114:117], v[170:173], v[186:189], v[114:117]
	v_mfma_f32_16x16x32_bf16 v[102:105], v[178:181], v[186:189], v[102:105]
	v_mfma_f32_16x16x32_bf16 v[94:97], v[170:173], v[194:197], v[94:97]
	v_mfma_f32_16x16x32_bf16 v[86:89], v[178:181], v[194:197], v[86:89]
	v_mfma_f32_16x16x32_bf16 v[82:85], v[170:173], v[216:219], v[82:85]
	v_mfma_f32_16x16x32_bf16 v[78:81], v[178:181], v[216:219], v[78:81]
	v_mfma_f32_16x16x32_bf16 v[74:77], v[170:173], v[224:227], v[74:77]
	v_mfma_f32_16x16x32_bf16 v[70:73], v[178:181], v[224:227], v[70:73]
	v_mfma_f32_16x16x32_bf16 v[114:117], v[174:177], v[190:193], v[114:117]
	v_mfma_f32_16x16x32_bf16 v[102:105], v[182:185], v[190:193], v[102:105]
	v_mfma_f32_16x16x32_bf16 v[94:97], v[174:177], v[212:215], v[94:97]
	v_mfma_f32_16x16x32_bf16 v[86:89], v[182:185], v[212:215], v[86:89]
	v_mfma_f32_16x16x32_bf16 v[82:85], v[174:177], v[220:223], v[82:85]
	v_mfma_f32_16x16x32_bf16 v[78:81], v[182:185], v[220:223], v[78:81]
	v_mfma_f32_16x16x32_bf16 v[74:77], v[174:177], v[228:231], v[74:77]
	v_mfma_f32_16x16x32_bf16 v[70:73], v[182:185], v[228:231], v[70:73]
	s_setprio 0
	s_barrier
	s_add_i32 s73, s73, s57
	v_lshl_add_u64 v[166:167], s[70:71], 0, v[138:139]
	s_mov_b32 m0, s73
	ds_read_b128 v[186:189], v149 offset:16384
	ds_read_b128 v[190:193], v149 offset:17408
	ds_read_b128 v[194:197], v149 offset:18432
	ds_read_b128 v[212:215], v149 offset:19456
	ds_read_b128 v[216:219], v149 offset:20480
	ds_read_b128 v[220:223], v149 offset:21504
	ds_read_b128 v[224:227], v149 offset:22528
	ds_read_b128 v[228:231], v149 offset:23552
	global_load_lds_dwordx4 v[166:167], off
	s_add_i32 m0, s73, 0x2000
	v_lshl_add_u64 v[236:237], s[70:71], 0, v[134:135]
	s_add_u32 s70, s70, s55
	s_addc_u32 s71, s71, 0
	s_add_i32 s72, s72, s57
	global_load_lds_dwordx4 v[236:237], off
	v_lshl_add_u64 v[238:239], s[70:71], 0, v[138:139]
	s_mov_b32 m0, s72
	v_lshl_add_u64 v[240:241], s[70:71], 0, v[134:135]
	global_load_lds_dwordx4 v[238:239], off
	s_add_i32 m0, s72, 0x2000
	v_lshl_add_u64 v[242:243], s[48:49], 0, v[140:141]
	global_load_lds_dwordx4 v[240:241], off
	s_mov_b32 m0, s58
	v_lshl_add_u64 v[244:245], s[48:49], 0, v[136:137]
	global_load_lds_dwordx4 v[242:243], off
	s_mov_b32 m0, s59
	s_nop 0
	global_load_lds_dwordx4 v[244:245], off
	s_waitcnt vmcnt(8)
	s_waitcnt lgkmcnt(0)
	s_barrier
; #define PG8_STAGE(bufoff, gbase, voff) do { _Pragma("unroll") for (int _i = 0; _i < 2; ++_i) \
;         __builtin_amdgcn_global_load_lds((const unsigned*)((const char*)(gbase) + (voff)[_i]), (LAS unsigned*)(lds + (bufoff) + ldsw + _i * 8192), 16, 0, 0); } while (0)
; #define PG8_LDA(dst, b, h) do { _Pragma("unroll") for (int m = 0; m < 4; ++m) _Pragma("unroll") for (int k = 0; k < 2; ++k) dst[m][k] = *(const LAS bf16x8*)(lds + PG8_SA(b, h) + aoff + m * 2048 + k * 1024); } while (0)
; #define PG8_LDB(dst, b, h) do { _Pragma("unroll") for (int n = 0; n < 2; ++n) _Pragma("unroll") for (int k = 0; k < 2; ++k) dst[n][k] = *(const LAS bf16x8*)(lds + PG8_SB(b, h) + boff + n * 2048 + k * 1024); } while (0)
; #define PG8_MMA(ai, bj, At, Bt) do { __builtin_amdgcn_s_setprio(1); _Pragma("unroll") for (int m = 0; m < 4; ++m) _Pragma("unroll") for (int n = 0; n < 2; ++n) _Pragma("unroll") for (int k = 0; k < 2; ++k) \
;         acc[ai][bj][m][n] = __builtin_amdgcn_mfma_f32_16x16x32_bf16(Bt[n][k], At[m][k], acc[ai][bj][m][n], 0, 0, 0); __builtin_amdgcn_s_setprio(0); } while (0)
; #define PG8_WAIT_V(n) asm volatile("s_waitcnt vmcnt(" #n ")" ::: "memory")
; #define PG8_WAIT_L(n) asm volatile("s_waitcnt lgkmcnt(" #n ")" ::: "memory")
; #define PG8_BAR __builtin_amdgcn_s_barrier()
; #define PG8_SCHED __builtin_amdgcn_sched_barrier(0)
; template <class Epi, class Sched>
; __device__ __forceinline__ void gemm_phase(LAS unsigned char* lds, const Gemm g, const Sched& S, const Epi& E) {
;     ...
;             PG8_WAIT_V(8); PG8_WAIT_L(0); PG8_BAR; PG8_MMA(1, 0, At, B0); PG8_MMA(1, 1, At, B1); PG8_BAR; PG8_SCHED;
;             PG8_LDB(B0, 1, 0); PG8_LDB(B1, 1, 1); PG8_SCHED; PG8_LDA(At, 1, 0); PG8_STAGE(PG8_SA(0, 1), a2 + hstepA, voffA);
;             PG8_WAIT_V(8); PG8_WAIT_L(0); PG8_BAR; PG8_MMA(0, 0, At, B0); PG8_MMA(0, 1, At, B1); PG8_BAR; PG8_SCHED;
	s_setprio 1
	v_mfma_f32_16x16x32_bf16 v[66:69], v[150:153], v[186:189], v[66:69]
	v_mfma_f32_16x16x32_bf16 v[62:65], v[158:161], v[186:189], v[62:65]
	v_mfma_f32_16x16x32_bf16 v[58:61], v[150:153], v[194:197], v[58:61]
	v_mfma_f32_16x16x32_bf16 v[54:57], v[158:161], v[194:197], v[54:57]
	v_mfma_f32_16x16x32_bf16 v[50:53], v[150:153], v[216:219], v[50:53]
	v_mfma_f32_16x16x32_bf16 v[42:45], v[158:161], v[216:219], v[42:45]
	v_mfma_f32_16x16x32_bf16 v[34:37], v[150:153], v[224:227], v[34:37]
	v_mfma_f32_16x16x32_bf16 v[26:29], v[158:161], v[224:227], v[26:29]
	v_mfma_f32_16x16x32_bf16 v[66:69], v[154:157], v[190:193], v[66:69]
	v_mfma_f32_16x16x32_bf16 v[62:65], v[162:165], v[190:193], v[62:65]
	v_mfma_f32_16x16x32_bf16 v[58:61], v[154:157], v[212:215], v[58:61]
	v_mfma_f32_16x16x32_bf16 v[54:57], v[162:165], v[212:215], v[54:57]
	v_mfma_f32_16x16x32_bf16 v[50:53], v[154:157], v[220:223], v[50:53]
	v_mfma_f32_16x16x32_bf16 v[42:45], v[162:165], v[220:223], v[42:45]
	v_mfma_f32_16x16x32_bf16 v[34:37], v[154:157], v[228:231], v[34:37]
	v_mfma_f32_16x16x32_bf16 v[26:29], v[162:165], v[228:231], v[26:29]
	v_mfma_f32_16x16x32_bf16 v[46:49], v[170:173], v[186:189], v[46:49]
	v_mfma_f32_16x16x32_bf16 v[38:41], v[178:181], v[186:189], v[38:41]
	v_mfma_f32_16x16x32_bf16 v[30:33], v[170:173], v[194:197], v[30:33]
	v_mfma_f32_16x16x32_bf16 v[22:25], v[178:181], v[194:197], v[22:25]
	v_mfma_f32_16x16x32_bf16 v[18:21], v[170:173], v[216:219], v[18:21]
	v_mfma_f32_16x16x32_bf16 v[14:17], v[178:181], v[216:219], v[14:17]
	v_mfma_f32_16x16x32_bf16 v[10:13], v[170:173], v[224:227], v[10:13]
	v_mfma_f32_16x16x32_bf16 v[6:9], v[178:181], v[224:227], v[6:9]
	v_mfma_f32_16x16x32_bf16 v[46:49], v[174:177], v[190:193], v[46:49]
	v_mfma_f32_16x16x32_bf16 v[38:41], v[182:185], v[190:193], v[38:41]
	v_mfma_f32_16x16x32_bf16 v[30:33], v[174:177], v[212:215], v[30:33]
	v_mfma_f32_16x16x32_bf16 v[22:25], v[182:185], v[212:215], v[22:25]
	v_mfma_f32_16x16x32_bf16 v[18:21], v[174:177], v[220:223], v[18:21]
	v_mfma_f32_16x16x32_bf16 v[14:17], v[182:185], v[220:223], v[14:17]
	v_mfma_f32_16x16x32_bf16 v[10:13], v[174:177], v[228:231], v[10:13]
	v_mfma_f32_16x16x32_bf16 v[6:9], v[182:185], v[228:231], v[6:9]
	s_setprio 0
	s_barrier
	s_add_i32 s70, 0, 0x18000
	v_add_u32_e32 v4, s70, v148
	s_add_i32 s71, 0, 0x1c000
	ds_read_b128 v[150:153], v4
	ds_read_b128 v[154:157], v4 offset:1024
	ds_read_b128 v[158:161], v4 offset:2048
	ds_read_b128 v[162:165], v4 offset:3072
	v_add_u32_e32 v4, s71, v148
	ds_read_b128 v[170:173], v4
	ds_read_b128 v[174:177], v4 offset:1024
	ds_read_b128 v[178:181], v4 offset:2048
	ds_read_b128 v[182:185], v4 offset:3072
	s_add_u32 s48, s48, s34
	s_addc_u32 s49, s49, 0
	s_mov_b32 m0, s60
	v_lshl_add_u64 v[246:247], s[48:49], 0, v[140:141]
	ds_read_b128 v[186:189], v149 offset:32768
	ds_read_b128 v[190:193], v149 offset:33792
	ds_read_b128 v[194:197], v149 offset:34816
	ds_read_b128 v[212:215], v149 offset:35840
	ds_read_b128 v[216:219], v149 offset:36864
	ds_read_b128 v[220:223], v149 offset:37888
	ds_read_b128 v[224:227], v149 offset:38912
	ds_read_b128 v[228:231], v149 offset:39936
	global_load_lds_dwordx4 v[246:247], off
	v_lshl_add_u64 v[246:247], s[48:49], 0, v[136:137]
	s_mov_b32 m0, s61
	s_nop 0
	global_load_lds_dwordx4 v[246:247], off
	s_waitcnt vmcnt(8)
	s_waitcnt lgkmcnt(0)
	s_barrier
	s_setprio 1
	v_mfma_f32_16x16x32_bf16 v[130:133], v[150:153], v[186:189], v[130:133]
	v_mfma_f32_16x16x32_bf16 v[126:129], v[158:161], v[186:189], v[126:129]
	v_mfma_f32_16x16x32_bf16 v[122:125], v[150:153], v[194:197], v[122:125]
	v_mfma_f32_16x16x32_bf16 v[118:121], v[158:161], v[194:197], v[118:121]
	v_mfma_f32_16x16x32_bf16 v[110:113], v[150:153], v[216:219], v[110:113]
	v_mfma_f32_16x16x32_bf16 v[106:109], v[158:161], v[216:219], v[106:109]
	v_mfma_f32_16x16x32_bf16 v[98:101], v[150:153], v[224:227], v[98:101]
	v_mfma_f32_16x16x32_bf16 v[90:93], v[158:161], v[224:227], v[90:93]
	v_mfma_f32_16x16x32_bf16 v[130:133], v[154:157], v[190:193], v[130:133]
	v_mfma_f32_16x16x32_bf16 v[126:129], v[162:165], v[190:193], v[126:129]
	v_mfma_f32_16x16x32_bf16 v[122:125], v[154:157], v[212:215], v[122:125]
	v_mfma_f32_16x16x32_bf16 v[118:121], v[162:165], v[212:215], v[118:121]
	v_mfma_f32_16x16x32_bf16 v[110:113], v[154:157], v[220:223], v[110:113]
	v_mfma_f32_16x16x32_bf16 v[106:109], v[162:165], v[220:223], v[106:109]
	v_mfma_f32_16x16x32_bf16 v[98:101], v[154:157], v[228:231], v[98:101]
	v_mfma_f32_16x16x32_bf16 v[90:93], v[162:165], v[228:231], v[90:93]
	v_mfma_f32_16x16x32_bf16 v[114:117], v[170:173], v[186:189], v[114:117]
	v_mfma_f32_16x16x32_bf16 v[102:105], v[178:181], v[186:189], v[102:105]
	v_mfma_f32_16x16x32_bf16 v[94:97], v[170:173], v[194:197], v[94:97]
	v_mfma_f32_16x16x32_bf16 v[86:89], v[178:181], v[194:197], v[86:89]
	v_mfma_f32_16x16x32_bf16 v[82:85], v[170:173], v[216:219], v[82:85]
	v_mfma_f32_16x16x32_bf16 v[78:81], v[178:181], v[216:219], v[78:81]
	v_mfma_f32_16x16x32_bf16 v[74:77], v[170:173], v[224:227], v[74:77]
	v_mfma_f32_16x16x32_bf16 v[70:73], v[178:181], v[224:227], v[70:73]
	v_mfma_f32_16x16x32_bf16 v[114:117], v[174:177], v[190:193], v[114:117]
	v_mfma_f32_16x16x32_bf16 v[102:105], v[182:185], v[190:193], v[102:105]
	v_mfma_f32_16x16x32_bf16 v[94:97], v[174:177], v[212:215], v[94:97]
	v_mfma_f32_16x16x32_bf16 v[86:89], v[182:185], v[212:215], v[86:89]
	v_mfma_f32_16x16x32_bf16 v[82:85], v[174:177], v[220:223], v[82:85]
	v_mfma_f32_16x16x32_bf16 v[78:81], v[182:185], v[220:223], v[78:81]
	v_mfma_f32_16x16x32_bf16 v[74:77], v[174:177], v[228:231], v[74:77]
	v_mfma_f32_16x16x32_bf16 v[70:73], v[182:185], v[228:231], v[70:73]
	s_setprio 0
	s_barrier
; #define PG8_STAGE(bufoff, gbase, voff) do { _Pragma("unroll") for (int _i = 0; _i < 2; ++_i) \
;         __builtin_amdgcn_global_load_lds((const unsigned*)((const char*)(gbase) + (voff)[_i]), (LAS unsigned*)(lds + (bufoff) + ldsw + _i * 8192), 16, 0, 0); } while (0)
; #define PG8_LDA(dst, b, h) do { _Pragma("unroll") for (int m = 0; m < 4; ++m) _Pragma("unroll") for (int k = 0; k < 2; ++k) dst[m][k] = *(const LAS bf16x8*)(lds + PG8_SA(b, h) + aoff + m * 2048 + k * 1024); } while (0)
; #define PG8_MMA(ai, bj, At, Bt) do { __builtin_amdgcn_s_setprio(1); _Pragma("unroll") for (int m = 0; m < 4; ++m) _Pragma("unroll") for (int n = 0; n < 2; ++n) _Pragma("unroll") for (int k = 0; k < 2; ++k) \
;         acc[ai][bj][m][n] = __builtin_amdgcn_mfma_f32_16x16x32_bf16(Bt[n][k], At[m][k], acc[ai][bj][m][n], 0, 0, 0); __builtin_amdgcn_s_setprio(0); } while (0)
; #define PG8_WAIT_V(n) asm volatile("s_waitcnt vmcnt(" #n ")" ::: "memory")
; #define PG8_WAIT_L(n) asm volatile("s_waitcnt lgkmcnt(" #n ")" ::: "memory")
; #define PG8_BAR __builtin_amdgcn_s_barrier()
; #define PG8_SCHED __builtin_amdgcn_sched_barrier(0)
; template <class Epi, class Sched>
; __device__ __forceinline__ void gemm_phase(LAS unsigned char* lds, const Gemm g, const Sched& S, const Epi& E) {
;     ...
;             PG8_LDA(At, 1, 1); PG8_STAGE(PG8_SB(1, 0), b3, voffB); PG8_STAGE(PG8_SB(1, 1), b3 + hstepB, voffB); PG8_STAGE(PG8_SA(1, 0), a3, voffA);
;             PG8_WAIT_V(8); PG8_WAIT_L(0); PG8_BAR; PG8_MMA(1, 0, At, B0); PG8_MMA(1, 1, At, B1); PG8_BAR; PG8_SCHED;
;         }
;         if (wr == 0) PG8_BAR;
	s_add_i32 s48, s70, s57
	v_lshl_add_u64 v[166:167], v[166:167], 0, s[36:37]
	s_mov_b32 m0, s48
	ds_read_b128 v[186:189], v149 offset:49152
	ds_read_b128 v[190:193], v149 offset:50176
	ds_read_b128 v[194:197], v149 offset:51200
	ds_read_b128 v[212:215], v149 offset:52224
	ds_read_b128 v[216:219], v149 offset:53248
	ds_read_b128 v[220:223], v149 offset:54272
	ds_read_b128 v[224:227], v149 offset:55296
	ds_read_b128 v[228:231], v149 offset:56320
	global_load_lds_dwordx4 v[166:167], off
	v_lshl_add_u64 v[166:167], v[236:237], 0, s[36:37]
	s_add_i32 m0, s48, 0x2000
	s_add_i32 s48, s71, s57
	global_load_lds_dwordx4 v[166:167], off
	v_lshl_add_u64 v[166:167], v[238:239], 0, s[36:37]
	s_mov_b32 m0, s48
	s_nop 0
	global_load_lds_dwordx4 v[166:167], off
	v_lshl_add_u64 v[166:167], v[240:241], 0, s[36:37]
	s_add_i32 m0, s48, 0x2000
	s_nop 0
	global_load_lds_dwordx4 v[166:167], off
	v_lshl_add_u64 v[166:167], v[242:243], 0, s[36:37]
	s_mov_b32 m0, s62
	s_nop 0
	global_load_lds_dwordx4 v[166:167], off
	v_lshl_add_u64 v[166:167], v[244:245], 0, s[36:37]
	s_mov_b32 m0, s63
	s_nop 0
	global_load_lds_dwordx4 v[166:167], off
	s_waitcnt vmcnt(8)
	s_waitcnt lgkmcnt(0)
	s_barrier
	s_setprio 1
	v_mfma_f32_16x16x32_bf16 v[66:69], v[150:153], v[186:189], v[66:69]
	v_mfma_f32_16x16x32_bf16 v[62:65], v[158:161], v[186:189], v[62:65]
	v_mfma_f32_16x16x32_bf16 v[58:61], v[150:153], v[194:197], v[58:61]
	v_mfma_f32_16x16x32_bf16 v[54:57], v[158:161], v[194:197], v[54:57]
	v_mfma_f32_16x16x32_bf16 v[50:53], v[150:153], v[216:219], v[50:53]
	v_mfma_f32_16x16x32_bf16 v[42:45], v[158:161], v[216:219], v[42:45]
	v_mfma_f32_16x16x32_bf16 v[34:37], v[150:153], v[224:227], v[34:37]
	v_mfma_f32_16x16x32_bf16 v[26:29], v[158:161], v[224:227], v[26:29]
	v_mfma_f32_16x16x32_bf16 v[66:69], v[154:157], v[190:193], v[66:69]
	v_mfma_f32_16x16x32_bf16 v[62:65], v[162:165], v[190:193], v[62:65]
	v_mfma_f32_16x16x32_bf16 v[58:61], v[154:157], v[212:215], v[58:61]
	v_mfma_f32_16x16x32_bf16 v[54:57], v[162:165], v[212:215], v[54:57]
	v_mfma_f32_16x16x32_bf16 v[50:53], v[154:157], v[220:223], v[50:53]
	v_mfma_f32_16x16x32_bf16 v[42:45], v[162:165], v[220:223], v[42:45]
	v_mfma_f32_16x16x32_bf16 v[34:37], v[154:157], v[228:231], v[34:37]
	v_mfma_f32_16x16x32_bf16 v[26:29], v[162:165], v[228:231], v[26:29]
	v_mfma_f32_16x16x32_bf16 v[46:49], v[170:173], v[186:189], v[46:49]
	v_mfma_f32_16x16x32_bf16 v[38:41], v[178:181], v[186:189], v[38:41]
	v_mfma_f32_16x16x32_bf16 v[30:33], v[170:173], v[194:197], v[30:33]
	v_mfma_f32_16x16x32_bf16 v[22:25], v[178:181], v[194:197], v[22:25]
	v_mfma_f32_16x16x32_bf16 v[18:21], v[170:173], v[216:219], v[18:21]
	v_mfma_f32_16x16x32_bf16 v[14:17], v[178:181], v[216:219], v[14:17]
	v_mfma_f32_16x16x32_bf16 v[10:13], v[170:173], v[224:227], v[10:13]
	v_mfma_f32_16x16x32_bf16 v[6:9], v[178:181], v[224:227], v[6:9]
	v_mfma_f32_16x16x32_bf16 v[46:49], v[174:177], v[190:193], v[46:49]
	v_mfma_f32_16x16x32_bf16 v[38:41], v[182:185], v[190:193], v[38:41]
	v_mfma_f32_16x16x32_bf16 v[30:33], v[174:177], v[212:215], v[30:33]
	v_mfma_f32_16x16x32_bf16 v[22:25], v[182:185], v[212:215], v[22:25]
	v_mfma_f32_16x16x32_bf16 v[18:21], v[174:177], v[220:223], v[18:21]
	v_mfma_f32_16x16x32_bf16 v[14:17], v[182:185], v[220:223], v[14:17]
	v_mfma_f32_16x16x32_bf16 v[10:13], v[174:177], v[228:231], v[10:13]
	v_mfma_f32_16x16x32_bf16 v[6:9], v[182:185], v[228:231], v[6:9]
	s_setprio 0
	s_barrier
	s_add_u32 s46, s46, 0x100
	s_addc_u32 s47, s47, 0
	v_lshl_add_u64 v[146:147], v[146:147], 0, s[30:31]
	v_lshl_add_u64 v[2:3], v[2:3], 0, s[30:31]
	s_cmp_ge_u32 s43, s64
	s_mov_b32 s48, s43
	s_cbranch_scc0 .LBB0_1009
	s_and_b64 vcc, exec, s[28:29]
	s_cbranch_vccz .LBB0_1012
	s_barrier
